# residual GEMM prologues: wait before accumulator-init unpack counted down to vmcnt(8); plus next-unit mapping shortcut in FFN-up and permlane32_swap for the xor-32 row-sum exchange; rest as peeled-zer
# baseline (speedup 1.0000x reference)
; __device__ __forceinline__ float bf_lo(unsigned w) { return __uint_as_float(w << 16); }
; __device__ __forceinline__ float bf_hi(unsigned w) { return __uint_as_float(w & 0xffff0000u); }
; #define PG8_STAGE(bufoff, gbase, voff) do { _Pragma("unroll") for (int _i = 0; _i < 2; ++_i) \
;         __builtin_amdgcn_global_load_lds((const unsigned*)((const char*)(gbase) + (voff)[_i]), (PG8_LAS unsigned*)(lds + (bufoff) + ldsw + _i * 8192), 16, 0, 0); } while (0)
; #define PG8_WAIT_V(n) asm volatile("s_waitcnt vmcnt(" #n ")" ::: "memory")
; #define PG8_BAR __builtin_amdgcn_s_barrier()
; __device__ __forceinline__ void acc_from_xb(AccT& acc, const bf16_t* xb, const Unit& u, int wr, int wc, int fr, int fq) {
;     const unsigned off0 = (unsigned)(u.pm * BM + wr * 64 + fr) * DM + u.pn * BM + wc * 32 + 8 * fq;
; #pragma unroll
;     for (int ai = 0; ai < 2; ++ai)
; #pragma unroll
;         for (int m = 0; m < 4; ++m)
; #pragma unroll
;             for (int bj = 0; bj < 2; ++bj) { const u32x4 w = *(const u32x4*)(xb + off0 + (unsigned)(ai * HALF + m * 16) * DM + bj * HALF);
;                 acc[ai][bj][m][0] = (f32x4){bf_lo(w.x), bf_hi(w.x), bf_lo(w.y), bf_hi(w.y)}; acc[ai][bj][m][1] = (f32x4){bf_lo(w.z), bf_hi(w.z), bf_lo(w.w), bf_hi(w.w)}; }
; template <class Epi, class Sched, bool ALIGN_EPI = false, bool SP2 = false>
; __device__ __forceinline__ void gemm_phase(PG8_LAS unsigned char* lds, const Gemm g, const Sched& S, const Epi& E, const int wid) {
;     ...
;     if constexpr (SP2) {
;         PG8_STAGE(PG8_SB(0, 0), cB, voffB); PG8_STAGE(PG8_SB(0, 1), cB + hstepB, voffB); PG8_STAGE(PG8_SA(0, 0), cA, voffA); PG8_STAGE(PG8_SA(0, 1), cA + hstepA, voffA);
;         if (wr == 1) PG8_BAR;
;         PG8_WAIT_V(2); PG8_BAR;
;         PG8_STAGE(PG8_SB(1, 0), cB + kstep, voffB); PG8_STAGE(PG8_SA(1, 0), cA + kstep, voffA); PG8_STAGE(PG8_SB(1, 1), cB + hstepB + kstep, voffB);
;         PG8_WAIT_V(6); PG8_BAR;
.LBB0_395:
	s_mov_b64 s[26:27], 0x80
	s_waitcnt vmcnt(8)
	v_lshlrev_b32_e32 v84, 16, v36
	v_and_b32_e32 v85, 0xffff0000, v36
	v_lshlrev_b32_e32 v86, 16, v37
	v_and_b32_e32 v87, 0xffff0000, v37
	s_add_i32 m0, s11, 0x18000
	v_lshl_add_u64 v[36:37], v[142:143], 0, s[26:27]
	s_waitcnt vmcnt(2)
	s_barrier
	global_load_lds_dwordx4 v[36:37], off
	v_lshl_add_u64 v[36:37], v[140:141], 0, s[26:27]
	s_add_i32 m0, s11, 0x1a000
	s_add_i32 s59, s11, 0x8000
	s_add_i32 s60, s11, 0xa000
	global_load_lds_dwordx4 v[36:37], off
	v_lshl_add_u64 v[36:37], v[138:139], 0, s[26:27]
	s_mov_b32 m0, s59
	s_add_u32 s6, s24, 0x40080
	global_load_lds_dwordx4 v[36:37], off
	v_lshl_add_u64 v[36:37], v[136:137], 0, s[26:27]
	s_mov_b32 m0, s60
	s_addc_u32 s7, s25, 0
	global_load_lds_dwordx4 v[36:37], off
	s_add_i32 m0, s11, 0x1c000
	v_lshl_add_u64 v[36:37], s[6:7], 0, v[134:135]
	global_load_lds_dwordx4 v[36:37], off
	v_lshl_add_u64 v[36:37], s[6:7], 0, v[132:133]
	s_add_i32 m0, s11, 0x1e000
	v_or_b32_e32 v136, s72, v146
	global_load_lds_dwordx4 v[36:37], off
	v_lshlrev_b32_e32 v137, 6, v136
	v_and_b32_e32 v138, 48, v144
	s_movk_i32 s6, 0x3c0
	v_and_or_b32 v137, v137, s6, v138
	v_and_b32_e32 v139, 0xfffffc00, v145
	v_readlane_b32 s6, v250, 27
	v_lshlrev_b32_e32 v136, 2, v136
	v_and_b32_e32 v136, 32, v136
	v_add_u32_e32 v140, s6, v139
	v_bitop3_b32 v155, v137, v140, v136 bitop3:0xde
	v_lshl_or_b32 v136, v146, 6, v138
	v_readlane_b32 s6, v250, 35
	v_lshlrev_b32_e32 v138, 2, v146
	v_and_b32_e32 v138, 32, v138
	v_add_u32_e32 v137, s6, v139
	v_bitop3_b32 v148, v136, v137, v138 bitop3:0xde
	v_lshlrev_b32_e32 v136, 14, v149
	v_lshlrev_b32_e32 v138, 14, v152
	v_and_b32_e32 v136, 0xffff8000, v136
	v_and_b32_e32 v138, 0xffff8000, v138
	s_waitcnt vmcnt(6)
	v_lshl_add_u32 v136, v150, 11, v136
	v_and_b32_e32 v137, 1, v149
	v_lshl_add_u32 v138, v153, 11, v138
	v_and_b32_e32 v139, 1, v152
	s_cmp_gt_i32 s49, 0
	v_lshl_or_b32 v136, v137, 6, v136
	v_lshl_or_b32 v138, v139, 6, v138
	v_lshlrev_b32_e32 v124, 16, v60
	v_and_b32_e32 v125, 0xffff0000, v60
	v_lshlrev_b32_e32 v126, 16, v61
	v_and_b32_e32 v127, 0xffff0000, v61
	v_lshlrev_b32_e32 v120, 16, v62
	v_and_b32_e32 v121, 0xffff0000, v62
	v_lshlrev_b32_e32 v122, 16, v63
	v_and_b32_e32 v123, 0xffff0000, v63
	v_lshlrev_b32_e32 v116, 16, v56
	v_and_b32_e32 v117, 0xffff0000, v56
	v_lshlrev_b32_e32 v118, 16, v57
	v_and_b32_e32 v119, 0xffff0000, v57
	v_lshlrev_b32_e32 v112, 16, v58
	v_and_b32_e32 v113, 0xffff0000, v58
	v_lshlrev_b32_e32 v114, 16, v59
	v_and_b32_e32 v115, 0xffff0000, v59
	v_lshlrev_b32_e32 v108, 16, v52
	v_and_b32_e32 v109, 0xffff0000, v52
	v_lshlrev_b32_e32 v110, 16, v53
	v_and_b32_e32 v111, 0xffff0000, v53
	v_lshlrev_b32_e32 v104, 16, v54
	v_and_b32_e32 v105, 0xffff0000, v54
	v_lshlrev_b32_e32 v106, 16, v55
	v_and_b32_e32 v107, 0xffff0000, v55
	v_lshlrev_b32_e32 v96, 16, v48
	v_and_b32_e32 v97, 0xffff0000, v48
	v_lshlrev_b32_e32 v98, 16, v49
	v_and_b32_e32 v99, 0xffff0000, v49
	v_lshlrev_b32_e32 v88, 16, v50
	v_and_b32_e32 v89, 0xffff0000, v50
	v_lshlrev_b32_e32 v90, 16, v51
	v_and_b32_e32 v91, 0xffff0000, v51
	v_lshlrev_b32_e32 v100, 16, v44
	v_and_b32_e32 v101, 0xffff0000, v44
	v_lshlrev_b32_e32 v102, 16, v45
	v_and_b32_e32 v103, 0xffff0000, v45
	v_lshlrev_b32_e32 v92, 16, v46
	v_and_b32_e32 v93, 0xffff0000, v46
	v_lshlrev_b32_e32 v94, 16, v47
	v_and_b32_e32 v95, 0xffff0000, v47
	v_lshlrev_b32_e32 v80, 16, v40
	v_and_b32_e32 v81, 0xffff0000, v40
	v_lshlrev_b32_e32 v82, 16, v41
	v_and_b32_e32 v83, 0xffff0000, v41
	v_lshlrev_b32_e32 v72, 16, v42
	v_and_b32_e32 v73, 0xffff0000, v42
	v_lshlrev_b32_e32 v74, 16, v43
	v_and_b32_e32 v75, 0xffff0000, v43
	v_lshlrev_b32_e32 v76, 16, v38
	v_and_b32_e32 v77, 0xffff0000, v38
	v_lshlrev_b32_e32 v78, 16, v39
	v_and_b32_e32 v79, 0xffff0000, v39
	v_lshlrev_b32_e32 v68, 16, v28
	v_and_b32_e32 v69, 0xffff0000, v28
	v_lshlrev_b32_e32 v70, 16, v29
	v_and_b32_e32 v71, 0xffff0000, v29
	v_lshlrev_b32_e32 v64, 16, v30
	v_and_b32_e32 v65, 0xffff0000, v30
	v_lshlrev_b32_e32 v66, 16, v31
	v_and_b32_e32 v67, 0xffff0000, v31
	v_lshlrev_b32_e32 v52, 16, v20
	v_and_b32_e32 v53, 0xffff0000, v20
	v_lshlrev_b32_e32 v54, 16, v21
	v_and_b32_e32 v55, 0xffff0000, v21
	v_lshlrev_b32_e32 v40, 16, v22
	v_and_b32_e32 v41, 0xffff0000, v22
	v_lshlrev_b32_e32 v42, 16, v23
	v_and_b32_e32 v43, 0xffff0000, v23
	v_lshlrev_b32_e32 v20, 16, v8
	v_and_b32_e32 v21, 0xffff0000, v8
	v_lshlrev_b32_e32 v22, 16, v9
	v_and_b32_e32 v23, 0xffff0000, v9
	v_lshlrev_b32_e32 v8, 16, v10
	v_and_b32_e32 v9, 0xffff0000, v10
	v_lshlrev_b32_e32 v10, 16, v11
	v_and_b32_e32 v11, 0xffff0000, v11
	v_lshlrev_b32_e32 v28, 16, v12
	v_and_b32_e32 v29, 0xffff0000, v12
	v_lshlrev_b32_e32 v30, 16, v13
	v_and_b32_e32 v31, 0xffff0000, v13
	v_lshlrev_b32_e32 v12, 16, v14
	v_and_b32_e32 v13, 0xffff0000, v14
	v_lshlrev_b32_e32 v14, 16, v15
	v_and_b32_e32 v15, 0xffff0000, v15
	v_lshlrev_b32_e32 v56, 16, v32
	v_and_b32_e32 v57, 0xffff0000, v32
	v_lshlrev_b32_e32 v58, 16, v33
	v_and_b32_e32 v59, 0xffff0000, v33
	v_lshlrev_b32_e32 v44, 16, v34
	v_and_b32_e32 v45, 0xffff0000, v34
	v_lshlrev_b32_e32 v46, 16, v35
	v_and_b32_e32 v47, 0xffff0000, v35
	v_lshlrev_b32_e32 v60, 16, v24
	v_and_b32_e32 v61, 0xffff0000, v24
	v_lshlrev_b32_e32 v62, 16, v25
	v_and_b32_e32 v63, 0xffff0000, v25
	v_lshlrev_b32_e32 v48, 16, v26
	v_and_b32_e32 v49, 0xffff0000, v26
	v_lshlrev_b32_e32 v50, 16, v27
	v_and_b32_e32 v51, 0xffff0000, v27
	v_lshlrev_b32_e32 v32, 16, v16
	v_and_b32_e32 v33, 0xffff0000, v16
	v_lshlrev_b32_e32 v34, 16, v17
	v_and_b32_e32 v35, 0xffff0000, v17
	v_lshlrev_b32_e32 v16, 16, v18
	v_and_b32_e32 v17, 0xffff0000, v18
	v_lshlrev_b32_e32 v18, 16, v19
	v_and_b32_e32 v19, 0xffff0000, v19
	v_lshlrev_b32_e32 v36, 16, v4
	v_and_b32_e32 v37, 0xffff0000, v4
	v_lshlrev_b32_e32 v38, 16, v5
	v_and_b32_e32 v39, 0xffff0000, v5
	v_lshlrev_b32_e32 v24, 16, v6
	v_and_b32_e32 v25, 0xffff0000, v6
	v_lshlrev_b32_e32 v26, 16, v7
	v_and_b32_e32 v27, 0xffff0000, v7
	v_lshlrev_b32_e32 v4, 16, v0
	v_and_b32_e32 v5, 0xffff0000, v0
	v_lshlrev_b32_e32 v6, 16, v1
	v_and_b32_e32 v7, 0xffff0000, v1
	v_lshlrev_b32_e32 v0, 16, v2
	v_and_b32_e32 v1, 0xffff0000, v2
	v_lshlrev_b32_e32 v2, 16, v3
	v_and_b32_e32 v3, 0xffff0000, v3
	s_cselect_b64 s[28:29], -1, 0
	s_add_i32 s61, s49, -2
	v_lshl_add_u32 v136, v151, 1, v136
	v_mov_b32_e32 v137, v135
	v_lshl_add_u32 v138, v154, 1, v138
	v_mov_b32_e32 v139, v135
	v_mov_b64_e32 v[140:141], 0x100
	v_mov_b64_e32 v[142:143], 0xff
	s_add_i32 s62, 0, 0x10000
	s_add_i32 s63, 0, 0x14000
	v_add_u32_e32 v149, 0, v155
	s_barrier
	s_branch .LBB0_397

; __device__ __forceinline__ unsigned pk_bf16(float lo, float hi) { f32x2 v = {lo, hi}; return __builtin_bit_cast(unsigned, __builtin_convertvector(v, bf16v2)); }
; __device__ __forceinline__ void tile_row_ss(const AccT& acc, PG8_LAS float* P, int wr, int wc, int fr, int fq) {
;     ...
;         for (int m = 0; m < 4; ++m) { float ss = 0.f;
; #pragma unroll
;             for (int bj = 0; bj < 2; ++bj) { const f32x4 v0 = acc[ai][bj][m][0], v1 = acc[ai][bj][m][1];
;                 ss += (v0[0] * v0[0] + v0[1] * v0[1]) + (v0[2] * v0[2] + v0[3] * v0[3]) + (v1[0] * v1[0] + v1[1] * v1[1]) + (v1[2] * v1[2] + v1[3] * v1[3]); }
;             ss += __shfl_xor(ss, 16); ss += __shfl_xor(ss, 32);
;             if (fq == 0) P[(ai * HALF + wr * 64 + m * 16 + fr) * 4 + wc] = ss; }
;     __device__ __forceinline__ void fused(AccT& acc, const Unit& u, int wr, int wc, int fr, int fq, PG8_LAS unsigned char* lds, int wid, int lane) const {
;     ...
;                 for (int bj = 0; bj < 2; ++bj) { const f32x4 v0 = acc[ai][bj][m][0], v1 = acc[ai][bj][m][1];
;                     u32x4 w; w.x = pk_bf16(v0[0], v0[1]); w.y = pk_bf16(v0[2], v0[3]); w.z = pk_bf16(v1[0], v1[1]); w.w = pk_bf16(v1[2], v1[3]);
;                     *(u32x4*)(xb + off0 + (unsigned)(ai * HALF + m * 16) * DM + bj * HALF) = w; }
.LBB0_410:
	s_lshl_b32 s5, s10, 8
	s_add_i32 s6, s5, s72
	v_or_b32_e32 v128, s6, v146
	v_lshlrev_b32_e32 v128, 10, v128
	s_lshl_b32 s6, s4, 8
	v_add3_u32 v132, s6, v147, v128
	v_mov_b32_e32 v133, 0
	v_cvt_pk_bf16_f32 v128, v124, v125
	v_cvt_pk_bf16_f32 v129, v126, v127
	v_cvt_pk_bf16_f32 v130, v120, v121
	v_cvt_pk_bf16_f32 v131, v122, v123
	v_lshl_add_u64 v[132:133], v[132:133], 1, s[94:95]
	s_mov_b32 s6, 0x8000
	s_barrier
	global_store_dwordx4 v[132:133], v[128:131], off sc1
	v_add_co_u32_e32 v134, vcc, s6, v132
	s_nop 0
	v_cvt_pk_bf16_f32 v128, v116, v117
	v_cvt_pk_bf16_f32 v129, v118, v119
	v_cvt_pk_bf16_f32 v130, v112, v113
	v_cvt_pk_bf16_f32 v131, v114, v115
	global_store_dwordx4 v[132:133], v[128:131], off offset:256 sc1
	v_addc_co_u32_e32 v135, vcc, 0, v133, vcc
	s_nop 0
	v_cvt_pk_bf16_f32 v128, v108, v109
	v_cvt_pk_bf16_f32 v129, v110, v111
	v_cvt_pk_bf16_f32 v130, v104, v105
	v_cvt_pk_bf16_f32 v131, v106, v107
	global_store_dwordx4 v[134:135], v[128:131], off sc1
	s_mov_b32 s6, 0x10000
	v_mul_f32_e32 v125, v125, v125
	v_cvt_pk_bf16_f32 v128, v96, v97
	v_cvt_pk_bf16_f32 v129, v98, v99
	v_cvt_pk_bf16_f32 v130, v88, v89
	v_cvt_pk_bf16_f32 v131, v90, v91
	global_store_dwordx4 v[134:135], v[128:131], off offset:256 sc1
	v_add_co_u32_e32 v134, vcc, s6, v132
	s_nop 0
	v_cvt_pk_bf16_f32 v128, v100, v101
	v_cvt_pk_bf16_f32 v129, v102, v103
	v_cvt_pk_bf16_f32 v130, v92, v93
	v_cvt_pk_bf16_f32 v131, v94, v95
	v_addc_co_u32_e32 v135, vcc, 0, v133, vcc
	global_store_dwordx4 v[134:135], v[128:131], off sc1
	s_mov_b32 s6, 0x18000
	v_mul_f32_e32 v117, v117, v117
	v_cvt_pk_bf16_f32 v128, v80, v81
	v_cvt_pk_bf16_f32 v129, v82, v83
	v_cvt_pk_bf16_f32 v130, v72, v73
	v_cvt_pk_bf16_f32 v131, v74, v75
	global_store_dwordx4 v[134:135], v[128:131], off offset:256 sc1
	v_add_co_u32_e32 v134, vcc, s6, v132
	s_nop 0
	v_cvt_pk_bf16_f32 v128, v84, v85
	v_cvt_pk_bf16_f32 v129, v86, v87
	v_cvt_pk_bf16_f32 v130, v76, v77
	v_cvt_pk_bf16_f32 v131, v78, v79
	v_addc_co_u32_e32 v135, vcc, 0, v133, vcc
	global_store_dwordx4 v[134:135], v[128:131], off sc1
	s_mov_b32 s6, 0x40000
	v_fmac_f32_e32 v125, v124, v124
	v_cvt_pk_bf16_f32 v128, v68, v69
	v_cvt_pk_bf16_f32 v129, v70, v71
	v_cvt_pk_bf16_f32 v130, v64, v65
	v_cvt_pk_bf16_f32 v131, v66, v67
	global_store_dwordx4 v[134:135], v[128:131], off offset:256 sc1
	v_add_co_u32_e32 v134, vcc, s6, v132
	s_nop 0
	v_cvt_pk_bf16_f32 v128, v52, v53
	v_cvt_pk_bf16_f32 v129, v54, v55
	v_cvt_pk_bf16_f32 v130, v40, v41
	v_cvt_pk_bf16_f32 v131, v42, v43
	v_addc_co_u32_e32 v135, vcc, 0, v133, vcc
	global_store_dwordx4 v[134:135], v[128:131], off sc1
	s_mov_b32 s6, 0x48000
	v_mul_f32_e32 v124, v127, v127
	v_cvt_pk_bf16_f32 v128, v20, v21
	v_cvt_pk_bf16_f32 v129, v22, v23
	v_cvt_pk_bf16_f32 v130, v8, v9
	v_cvt_pk_bf16_f32 v131, v10, v11
	global_store_dwordx4 v[134:135], v[128:131], off offset:256 sc1
	v_add_co_u32_e32 v134, vcc, s6, v132
	s_nop 0
	v_cvt_pk_bf16_f32 v128, v28, v29
	v_cvt_pk_bf16_f32 v129, v30, v31
	v_cvt_pk_bf16_f32 v130, v12, v13
	v_cvt_pk_bf16_f32 v131, v14, v15
	v_addc_co_u32_e32 v135, vcc, 0, v133, vcc
	global_store_dwordx4 v[134:135], v[128:131], off sc1
	s_mov_b32 s6, 0x50000
	v_fmac_f32_e32 v117, v116, v116
	v_cvt_pk_bf16_f32 v128, v56, v57
	v_cvt_pk_bf16_f32 v129, v58, v59
	v_cvt_pk_bf16_f32 v130, v44, v45
	v_cvt_pk_bf16_f32 v131, v46, v47
	global_store_dwordx4 v[134:135], v[128:131], off offset:256 sc1
	v_add_co_u32_e32 v134, vcc, s6, v132
	s_nop 0
	v_cvt_pk_bf16_f32 v128, v60, v61
	v_cvt_pk_bf16_f32 v129, v62, v63
	v_cvt_pk_bf16_f32 v130, v48, v49
	v_cvt_pk_bf16_f32 v131, v50, v51
	v_addc_co_u32_e32 v135, vcc, 0, v133, vcc
	global_store_dwordx4 v[134:135], v[128:131], off sc1
	s_mov_b32 s6, 0x58000
	v_mul_f32_e32 v116, v119, v119
	v_cvt_pk_bf16_f32 v128, v32, v33
	v_cvt_pk_bf16_f32 v129, v34, v35
	v_cvt_pk_bf16_f32 v130, v16, v17
	v_cvt_pk_bf16_f32 v131, v18, v19
	global_store_dwordx4 v[134:135], v[128:131], off offset:256 sc1
	v_add_co_u32_e32 v134, vcc, s6, v132
	s_nop 0
	v_cvt_pk_bf16_f32 v128, v36, v37
	v_cvt_pk_bf16_f32 v129, v38, v39
	v_cvt_pk_bf16_f32 v130, v24, v25
	v_cvt_pk_bf16_f32 v131, v26, v27
	v_addc_co_u32_e32 v135, vcc, 0, v133, vcc
	global_store_dwordx4 v[134:135], v[128:131], off sc1
	v_fmac_f32_e32 v124, v126, v126
	v_mul_f32_e32 v121, v121, v121
	v_mbcnt_hi_u32_b32 v129, -1, v178
	v_fmac_f32_e32 v116, v118, v118
	v_mul_f32_e32 v113, v113, v113
	v_and_b32_e32 v136, 64, v129
	v_add_f32_e32 v124, v125, v124
	v_fmac_f32_e32 v121, v120, v120
	v_add_f32_e32 v116, v117, v116
	v_fmac_f32_e32 v113, v112, v112
	v_xor_b32_e32 v128, 16, v129
	v_add_u32_e32 v136, 64, v136
	v_add_f32_e32 v120, v121, v124
	v_mul_f32_e32 v121, v123, v123
	v_add_f32_e32 v112, v113, v116
	v_mul_f32_e32 v113, v115, v115
	v_cmp_lt_i32_e32 vcc, v128, v136
	v_fmac_f32_e32 v121, v122, v122
	v_fmac_f32_e32 v113, v114, v114
	v_cndmask_b32_e32 v128, v129, v128, vcc
	v_add_f32_e32 v120, v121, v120
	v_add_f32_e32 v112, v113, v112
	v_lshlrev_b32_e32 v128, 2, v128
	v_add_f32_e32 v113, v112, v120
	ds_bpermute_b32 v114, v128, v113
	v_xor_b32_e32 v112, 32, v129
	v_cmp_lt_i32_e32 vcc, v112, v136
	s_lshl_b32 s6, s48, 2
	v_cvt_pk_bf16_f32 v130, v4, v5
	v_cndmask_b32_e32 v112, v129, v112, vcc
	v_lshlrev_b32_e32 v112, 2, v112
	s_waitcnt lgkmcnt(0)
	v_add_f32_e32 v113, v113, v114
	v_mov_b32_e32 v114, v113
	s_nop 1
	v_permlane32_swap_b32_e32 v113, v114
	v_cvt_pk_bf16_f32 v131, v6, v7
	v_cvt_pk_bf16_f32 v132, v0, v1
	v_cvt_pk_bf16_f32 v133, v2, v3
	v_cmp_gt_u32_e32 vcc, 16, v144
	s_add_i32 s8, s6, 0
	global_store_dwordx4 v[134:135], v[130:133], off offset:256 sc1
	s_and_saveexec_b64 s[6:7], vcc
	s_cbranch_execz .LBB0_412
	s_lshl_b32 s9, s1, 10
	s_add_i32 s9, s8, s9
	v_add_u32_e32 v115, s9, v145
	s_waitcnt lgkmcnt(0)
	v_add_f32_e32 v113, v113, v114
	ds_write_b32 v115, v113
; __device__ __forceinline__ void tile_row_ss(const AccT& acc, PG8_LAS float* P, int wr, int wc, int fr, int fq) {
;     ...
;         for (int m = 0; m < 4; ++m) { float ss = 0.f;
; #pragma unroll
;             for (int bj = 0; bj < 2; ++bj) { const f32x4 v0 = acc[ai][bj][m][0], v1 = acc[ai][bj][m][1];
;                 ss += (v0[0] * v0[0] + v0[1] * v0[1]) + (v0[2] * v0[2] + v0[3] * v0[3]) + (v1[0] * v1[0] + v1[1] * v1[1]) + (v1[2] * v1[2] + v1[3] * v1[3]); }
;             ss += __shfl_xor(ss, 16); ss += __shfl_xor(ss, 32);
;             if (fq == 0) P[(ai * HALF + wr * 64 + m * 16 + fr) * 4 + wc] = ss; }
.LBB0_412:
	s_or_b64 exec, exec, s[6:7]
	v_mul_f32_e32 v109, v109, v109
	v_mul_f32_e32 v97, v97, v97
	v_fmac_f32_e32 v109, v108, v108
	v_mul_f32_e32 v108, v111, v111
	v_fmac_f32_e32 v97, v96, v96
	v_mul_f32_e32 v96, v99, v99
	v_fmac_f32_e32 v108, v110, v110
	v_mul_f32_e32 v105, v105, v105
	v_fmac_f32_e32 v96, v98, v98
	v_mul_f32_e32 v89, v89, v89
	v_add_f32_e32 v108, v109, v108
	v_fmac_f32_e32 v105, v104, v104
	v_add_f32_e32 v96, v97, v96
	v_fmac_f32_e32 v89, v88, v88
	v_add_f32_e32 v104, v105, v108
	v_mul_f32_e32 v105, v107, v107
	v_add_f32_e32 v88, v89, v96
	v_mul_f32_e32 v89, v91, v91
	v_fmac_f32_e32 v105, v106, v106
	v_fmac_f32_e32 v89, v90, v90
	v_add_f32_e32 v104, v105, v104
	v_add_f32_e32 v88, v89, v88
	v_add_f32_e32 v88, v88, v104
	ds_bpermute_b32 v89, v128, v88
	s_waitcnt lgkmcnt(0)
	v_add_f32_e32 v88, v88, v89
	v_mov_b32_e32 v89, v88
	s_nop 1
	v_permlane32_swap_b32_e32 v88, v89
	s_and_saveexec_b64 s[6:7], vcc
	s_cbranch_execz .LBB0_414
	s_lshl_b32 s9, s1, 10
	s_add_i32 s9, s8, s9
	v_add_u32_e32 v90, s9, v145
	s_waitcnt lgkmcnt(0)
	v_add_f32_e32 v88, v88, v89
	ds_write_b32 v90, v88 offset:256
.LBB0_414:
	s_or_b64 exec, exec, s[6:7]
	v_mul_f32_e32 v88, v101, v101
	s_waitcnt lgkmcnt(0)
	v_mul_f32_e32 v89, v103, v103
	v_mul_f32_e32 v81, v81, v81
	v_fmac_f32_e32 v88, v100, v100
	v_fmac_f32_e32 v89, v102, v102
	v_fmac_f32_e32 v81, v80, v80
	v_mul_f32_e32 v80, v83, v83
	v_add_f32_e32 v88, v88, v89
	v_mul_f32_e32 v89, v93, v93
	v_fmac_f32_e32 v80, v82, v82
	v_mul_f32_e32 v73, v73, v73
	v_fmac_f32_e32 v89, v92, v92
	v_add_f32_e32 v80, v81, v80
	v_fmac_f32_e32 v73, v72, v72
	v_add_f32_e32 v88, v89, v88
	v_mul_f32_e32 v89, v95, v95
	v_add_f32_e32 v72, v73, v80
	v_mul_f32_e32 v73, v75, v75
	v_fmac_f32_e32 v89, v94, v94
	v_fmac_f32_e32 v73, v74, v74
	v_add_f32_e32 v88, v89, v88
	v_add_f32_e32 v72, v73, v72
	v_add_f32_e32 v72, v72, v88
	ds_bpermute_b32 v73, v128, v72
	s_waitcnt lgkmcnt(0)
	v_add_f32_e32 v72, v72, v73
	v_mov_b32_e32 v73, v72
	s_nop 1
	v_permlane32_swap_b32_e32 v72, v73
	s_and_saveexec_b64 s[6:7], vcc
	s_cbranch_execz .LBB0_416
	s_lshl_b32 s9, s1, 10
	s_add_i32 s9, s8, s9
	v_add_u32_e32 v74, s9, v145
	s_waitcnt lgkmcnt(0)
	v_add_f32_e32 v72, v72, v73
	ds_write_b32 v74, v72 offset:512
.LBB0_416:
	s_or_b64 exec, exec, s[6:7]
	v_mul_f32_e32 v72, v85, v85
	s_waitcnt lgkmcnt(0)
	v_mul_f32_e32 v73, v87, v87
	v_mul_f32_e32 v69, v69, v69
	v_fmac_f32_e32 v72, v84, v84
	v_fmac_f32_e32 v73, v86, v86
	v_fmac_f32_e32 v69, v68, v68
	v_mul_f32_e32 v68, v71, v71
	v_add_f32_e32 v72, v72, v73
	v_mul_f32_e32 v73, v77, v77
	v_fmac_f32_e32 v68, v70, v70
	v_mul_f32_e32 v65, v65, v65
	v_fmac_f32_e32 v73, v76, v76
	v_add_f32_e32 v68, v69, v68
	v_fmac_f32_e32 v65, v64, v64
	v_add_f32_e32 v72, v73, v72
	v_mul_f32_e32 v73, v79, v79
	v_add_f32_e32 v64, v65, v68
	v_mul_f32_e32 v65, v67, v67
	v_fmac_f32_e32 v73, v78, v78
	v_fmac_f32_e32 v65, v66, v66
	v_add_f32_e32 v72, v73, v72
	v_add_f32_e32 v64, v65, v64
	v_add_f32_e32 v64, v64, v72
	ds_bpermute_b32 v65, v128, v64
	s_waitcnt lgkmcnt(0)
	v_add_f32_e32 v64, v64, v65
	v_mov_b32_e32 v65, v64
	s_nop 1
	v_permlane32_swap_b32_e32 v64, v65
	s_and_saveexec_b64 s[6:7], vcc
	s_cbranch_execz .LBB0_418
	s_lshl_b32 s9, s1, 10
	s_add_i32 s9, s8, s9
	v_add_u32_e32 v66, s9, v145
	s_waitcnt lgkmcnt(0)
	v_add_f32_e32 v64, v64, v65
	ds_write_b32 v66, v64 offset:768
; __device__ __forceinline__ void tile_row_ss(const AccT& acc, PG8_LAS float* P, int wr, int wc, int fr, int fq) {
;     ...
;         for (int m = 0; m < 4; ++m) { float ss = 0.f;
; #pragma unroll
;             for (int bj = 0; bj < 2; ++bj) { const f32x4 v0 = acc[ai][bj][m][0], v1 = acc[ai][bj][m][1];
;                 ss += (v0[0] * v0[0] + v0[1] * v0[1]) + (v0[2] * v0[2] + v0[3] * v0[3]) + (v1[0] * v1[0] + v1[1] * v1[1]) + (v1[2] * v1[2] + v1[3] * v1[3]); }
;             ss += __shfl_xor(ss, 16); ss += __shfl_xor(ss, 32);
;             if (fq == 0) P[(ai * HALF + wr * 64 + m * 16 + fr) * 4 + wc] = ss; }
.LBB0_418:
	s_or_b64 exec, exec, s[6:7]
	v_mul_f32_e32 v53, v53, v53
	v_mul_f32_e32 v21, v21, v21
	v_fmac_f32_e32 v53, v52, v52
	v_mul_f32_e32 v52, v55, v55
	v_fmac_f32_e32 v21, v20, v20
	v_mul_f32_e32 v20, v23, v23
	v_fmac_f32_e32 v52, v54, v54
	v_mul_f32_e32 v41, v41, v41
	v_fmac_f32_e32 v20, v22, v22
	v_mul_f32_e32 v9, v9, v9
	v_add_f32_e32 v52, v53, v52
	v_fmac_f32_e32 v41, v40, v40
	v_add_f32_e32 v20, v21, v20
	v_fmac_f32_e32 v9, v8, v8
	v_add_f32_e32 v40, v41, v52
	v_mul_f32_e32 v41, v43, v43
	v_add_f32_e32 v8, v9, v20
	v_mul_f32_e32 v9, v11, v11
	v_fmac_f32_e32 v41, v42, v42
	v_fmac_f32_e32 v9, v10, v10
	v_add_f32_e32 v40, v41, v40
	v_add_f32_e32 v8, v9, v8
	v_add_f32_e32 v8, v8, v40
	ds_bpermute_b32 v9, v128, v8
	s_waitcnt lgkmcnt(0)
	v_add_f32_e32 v8, v8, v9
	v_mov_b32_e32 v9, v8
	s_nop 1
	v_permlane32_swap_b32_e32 v8, v9
	s_and_saveexec_b64 s[6:7], vcc
	s_cbranch_execz .LBB0_420
	s_lshl_b32 s9, s1, 10
	s_add_i32 s9, s8, s9
	v_add_u32_e32 v10, s9, v145
	s_waitcnt lgkmcnt(0)
	v_add_f32_e32 v8, v8, v9
	ds_write_b32 v10, v8 offset:2048
.LBB0_420:
	s_or_b64 exec, exec, s[6:7]
	v_mul_f32_e32 v8, v29, v29
	s_waitcnt lgkmcnt(0)
	v_mul_f32_e32 v9, v31, v31
	v_fmac_f32_e32 v8, v28, v28
	v_fmac_f32_e32 v9, v30, v30
	v_add_f32_e32 v8, v8, v9
	v_mul_f32_e32 v9, v13, v13
	v_fmac_f32_e32 v9, v12, v12
	v_add_f32_e32 v8, v9, v8
	v_mul_f32_e32 v9, v15, v15
	v_fmac_f32_e32 v9, v14, v14
	v_add_f32_e32 v8, v9, v8
	v_mul_f32_e32 v9, v57, v57
	v_mul_f32_e32 v10, v59, v59
	v_fmac_f32_e32 v9, v56, v56
	v_fmac_f32_e32 v10, v58, v58
	v_add_f32_e32 v9, v9, v10
	v_mul_f32_e32 v10, v45, v45
	v_fmac_f32_e32 v10, v44, v44
	v_add_f32_e32 v9, v10, v9
	v_mul_f32_e32 v10, v47, v47
	v_fmac_f32_e32 v10, v46, v46
	v_add_f32_e32 v9, v10, v9
	v_add_f32_e32 v8, v9, v8
	ds_bpermute_b32 v9, v128, v8
	s_waitcnt lgkmcnt(0)
	v_add_f32_e32 v8, v8, v9
	v_mov_b32_e32 v9, v8
	s_nop 1
	v_permlane32_swap_b32_e32 v8, v9
	s_and_saveexec_b64 s[6:7], vcc
	s_cbranch_execz .LBB0_422
	s_lshl_b32 s9, s1, 10
	s_add_i32 s9, s8, s9
	v_add_u32_e32 v10, s9, v145
	s_waitcnt lgkmcnt(0)
	v_add_f32_e32 v8, v8, v9
	ds_write_b32 v10, v8 offset:2304
.LBB0_422:
	s_or_b64 exec, exec, s[6:7]
	v_mul_f32_e32 v8, v61, v61
	s_waitcnt lgkmcnt(0)
	v_mul_f32_e32 v9, v63, v63
	v_fmac_f32_e32 v8, v60, v60
	v_fmac_f32_e32 v9, v62, v62
	v_add_f32_e32 v8, v8, v9
	v_mul_f32_e32 v9, v49, v49
	v_fmac_f32_e32 v9, v48, v48
	v_add_f32_e32 v8, v9, v8
	v_mul_f32_e32 v9, v51, v51
	v_fmac_f32_e32 v9, v50, v50
	v_add_f32_e32 v8, v9, v8
	v_mul_f32_e32 v9, v33, v33
	v_mul_f32_e32 v10, v35, v35
	v_fmac_f32_e32 v9, v32, v32
	v_fmac_f32_e32 v10, v34, v34
	v_add_f32_e32 v9, v9, v10
	v_mul_f32_e32 v10, v17, v17
	v_fmac_f32_e32 v10, v16, v16
	v_add_f32_e32 v9, v10, v9
	v_mul_f32_e32 v10, v19, v19
	v_fmac_f32_e32 v10, v18, v18
	v_add_f32_e32 v9, v10, v9
	v_add_f32_e32 v8, v9, v8
	ds_bpermute_b32 v9, v128, v8
	s_waitcnt lgkmcnt(0)
	v_add_f32_e32 v8, v8, v9
	v_mov_b32_e32 v9, v8
	s_nop 1
	v_permlane32_swap_b32_e32 v8, v9
	s_and_saveexec_b64 s[6:7], vcc
	s_cbranch_execz .LBB0_424
	s_lshl_b32 s9, s1, 10
	s_add_i32 s9, s8, s9
	v_add_u32_e32 v10, s9, v145
	s_waitcnt lgkmcnt(0)
	v_add_f32_e32 v8, v8, v9
	ds_write_b32 v10, v8 offset:2560
.LBB0_424:
	s_or_b64 exec, exec, s[6:7]
	v_mul_f32_e32 v8, v37, v37
	s_waitcnt lgkmcnt(0)
	v_mul_f32_e32 v9, v39, v39
	v_mul_f32_e32 v5, v5, v5
	v_fmac_f32_e32 v8, v36, v36
	v_fmac_f32_e32 v9, v38, v38
	v_fmac_f32_e32 v5, v4, v4
	v_mul_f32_e32 v4, v7, v7
	v_add_f32_e32 v8, v8, v9
	v_mul_f32_e32 v9, v25, v25
	v_fmac_f32_e32 v4, v6, v6
	v_mul_f32_e32 v1, v1, v1
	v_fmac_f32_e32 v9, v24, v24
	v_add_f32_e32 v4, v5, v4
	v_fmac_f32_e32 v1, v0, v0
	v_add_f32_e32 v8, v9, v8
	v_mul_f32_e32 v9, v27, v27
	v_add_f32_e32 v0, v1, v4
	v_mul_f32_e32 v1, v3, v3
	v_fmac_f32_e32 v9, v26, v26
	v_fmac_f32_e32 v1, v2, v2
	v_add_f32_e32 v8, v9, v8
	v_add_f32_e32 v0, v1, v0
	v_add_f32_e32 v0, v0, v8
	ds_bpermute_b32 v1, v128, v0
	s_waitcnt lgkmcnt(0)
	v_add_f32_e32 v0, v0, v1
	v_mov_b32_e32 v1, v0
	s_nop 1
	v_permlane32_swap_b32_e32 v0, v1
	s_and_saveexec_b64 s[6:7], vcc
	s_cbranch_execz .LBB0_426
	s_lshl_b32 s9, s1, 10
	s_add_i32 s8, s8, s9
	v_add_u32_e32 v2, s8, v145
	s_waitcnt lgkmcnt(0)
	v_add_f32_e32 v0, v0, v1
	ds_write_b32 v2, v0 offset:2816

;     __host__ __device__ bool next(int i, Unit& u) const {
;         const long L = (long)i * G + c; if (L >= nwg) return false;
;         int wgid = (int)L; { const int q = nwg / NXCD, r = nwg % NXCD, xcd = wgid % NXCD, off = wgid / NXCD; wgid = (xcd < r ? xcd * (q + 1) : r * (q + 1) + (xcd - r) * q) + off; }
;         const int nig = WGM * nN, gid = wgid / nig, fm = gid * WGM, gsz = (nM - fm) < WGM ? (nM - fm) : WGM;
;         u.pm = fm + ((wgid % nig) % gsz); u.pn = (wgid % nig) / gsz; return true;
;     }
; template <class Epi, class Sched, bool ALIGN_EPI = false, bool SP2 = false>
; __device__ __forceinline__ void gemm_phase(PG8_LAS unsigned char* lds, const Gemm g, const Sched& S, const Epi& E, const int wid) {
;     ...
;         const bool has_next = S.next(ui + 1, nxt);
;         const char* nA = !has_next ? cA : nxt.pn >= g.swap_pn ? (const char*)g.A2 + (size_t)(nxt.pn - g.swap_pn) * tstepA : (const char*)g.A + (size_t)nxt.pm * tstepA + (g.bd ? (size_t)(nxt.pn >> 1) * 512 : 0);
;         const char* nB = !has_next ? cB : nxt.pn >= g.swap_pn ? (const char*)g.B2 + (size_t)nxt.pm * tstepB : (const char*)g.Bt + (size_t)nxt.pn * tstepB;
.LBB0_483:
	s_add_i32 s71, s71, 1
	s_mul_i32 s11, s21, s71
	s_mul_hi_u32 s44, s20, s71
	s_add_i32 s44, s44, s11
	s_mul_i32 s11, s20, s71
	s_add_u32 s52, s11, s2
	s_addc_u32 s53, s44, s3
	v_cmp_gt_i64_e32 vcc, s[52:53], v[150:151]
	v_cmp_lt_i64_e64 s[44:45], s[52:53], v[148:149]
	s_cbranch_vccnz .LBB0_485
	s_movk_i32 s9, 0xb1
	s_mov_b32 s60, 0x32000
	s_mov_b32 s50, s73
	s_add_i32 s10, s8, 4

; __device__ __forceinline__ float bf_lo(unsigned w) { return __uint_as_float(w << 16); }
; __device__ __forceinline__ float bf_hi(unsigned w) { return __uint_as_float(w & 0xffff0000u); }
; #define PG8_STAGE(bufoff, gbase, voff) do { _Pragma("unroll") for (int _i = 0; _i < 2; ++_i) \
;         __builtin_amdgcn_global_load_lds((const unsigned*)((const char*)(gbase) + (voff)[_i]), (PG8_LAS unsigned*)(lds + (bufoff) + ldsw + _i * 8192), 16, 0, 0); } while (0)
; #define PG8_WAIT_V(n) asm volatile("s_waitcnt vmcnt(" #n ")" ::: "memory")
; #define PG8_BAR __builtin_amdgcn_s_barrier()
; __device__ __forceinline__ void acc_from_xb(AccT& acc, const bf16_t* xb, const Unit& u, int wr, int wc, int fr, int fq) {
;     const unsigned off0 = (unsigned)(u.pm * BM + wr * 64 + fr) * DM + u.pn * BM + wc * 32 + 8 * fq;
; #pragma unroll
;     for (int ai = 0; ai < 2; ++ai)
; #pragma unroll
;         for (int m = 0; m < 4; ++m)
; #pragma unroll
;             for (int bj = 0; bj < 2; ++bj) { const u32x4 w = *(const u32x4*)(xb + off0 + (unsigned)(ai * HALF + m * 16) * DM + bj * HALF);
;                 acc[ai][bj][m][0] = (f32x4){bf_lo(w.x), bf_hi(w.x), bf_lo(w.y), bf_hi(w.y)}; acc[ai][bj][m][1] = (f32x4){bf_lo(w.z), bf_hi(w.z), bf_lo(w.w), bf_hi(w.w)}; }
; template <class Epi, class Sched, bool ALIGN_EPI = false, bool SP2 = false>
; __device__ __forceinline__ void gemm_phase(PG8_LAS unsigned char* lds, const Gemm g, const Sched& S, const Epi& E, const int wid) {
;     ...
;     if constexpr (SP2) {
;         PG8_STAGE(PG8_SB(0, 0), cB, voffB); PG8_STAGE(PG8_SB(0, 1), cB + hstepB, voffB); PG8_STAGE(PG8_SA(0, 0), cA, voffA); PG8_STAGE(PG8_SA(0, 1), cA + hstepA, voffA);
;         if (wr == 1) PG8_BAR;
;         PG8_WAIT_V(2); PG8_BAR;
;         PG8_STAGE(PG8_SB(1, 0), cB + kstep, voffB); PG8_STAGE(PG8_SA(1, 0), cA + kstep, voffA); PG8_STAGE(PG8_SB(1, 1), cB + hstepB + kstep, voffB);
;         PG8_WAIT_V(6); PG8_BAR;
.LBB0_560:
	s_waitcnt vmcnt(8)
	v_lshlrev_b32_e32 v116, 16, v56
	v_and_b32_e32 v117, 0xffff0000, v56
	v_lshlrev_b32_e32 v118, 16, v57
	v_and_b32_e32 v119, 0xffff0000, v57
	v_lshlrev_b32_e32 v112, 16, v58
	v_and_b32_e32 v113, 0xffff0000, v58
	v_lshlrev_b32_e32 v114, 16, v59
	v_and_b32_e32 v115, 0xffff0000, v59
	v_lshlrev_b32_e32 v92, 16, v44
	v_and_b32_e32 v93, 0xffff0000, v44
	v_lshlrev_b32_e32 v94, 16, v45
	v_and_b32_e32 v95, 0xffff0000, v45
	v_lshlrev_b32_e32 v88, 16, v46
	v_and_b32_e32 v89, 0xffff0000, v46
	v_lshlrev_b32_e32 v90, 16, v47
	v_and_b32_e32 v91, 0xffff0000, v47
	v_lshlrev_b32_e32 v56, 16, v16
	v_and_b32_e32 v57, 0xffff0000, v16
	v_lshlrev_b32_e32 v58, 16, v17
	v_and_b32_e32 v59, 0xffff0000, v17
	v_lshlrev_b32_e32 v44, 16, v18
	v_and_b32_e32 v45, 0xffff0000, v18
	v_lshlrev_b32_e32 v46, 16, v19
	v_and_b32_e32 v47, 0xffff0000, v19
	v_lshlrev_b32_e32 v16, 16, v6
	v_and_b32_e32 v17, 0xffff0000, v6
	v_lshlrev_b32_e32 v18, 16, v7
	v_and_b32_e32 v19, 0xffff0000, v7
	v_lshl_add_u64 v[6:7], s[10:11], 0, v[146:147]
	v_mov_b32_e32 v129, v147
	v_readlane_b32 s52, v249, 31
	v_lshlrev_b32_e32 v84, 16, v40
	v_and_b32_e32 v85, 0xffff0000, v40
	v_lshlrev_b32_e32 v86, 16, v41
	v_and_b32_e32 v87, 0xffff0000, v41
	v_lshl_add_u64 v[40:41], s[10:11], 0, v[128:129]
	v_mov_b32_e32 v133, v147
	v_readlane_b32 s53, v249, 32
	v_lshl_add_u64 v[6:7], v[6:7], 0, s[80:81]
	s_add_i32 m0, s67, 0x18000
	v_lshlrev_b32_e32 v72, 16, v42
	v_and_b32_e32 v73, 0xffff0000, v42
	v_lshlrev_b32_e32 v74, 16, v43
	v_and_b32_e32 v75, 0xffff0000, v43
	v_lshl_add_u64 v[42:43], s[52:53], 0, v[132:133]
	v_mov_b32_e32 v131, v147
	s_waitcnt vmcnt(2)
	s_barrier
	global_load_lds_dwordx4 v[6:7], off
	v_lshl_add_u64 v[6:7], v[40:41], 0, s[80:81]
	s_add_i32 m0, s67, 0x1a000
	s_add_i32 s71, s67, 0x8000
	s_add_i32 s72, s67, 0xa000
	v_lshlrev_b32_e32 v100, 16, v48
	v_and_b32_e32 v101, 0xffff0000, v48
	v_lshlrev_b32_e32 v102, 16, v49
	v_and_b32_e32 v103, 0xffff0000, v49
	v_lshl_add_u64 v[48:49], s[52:53], 0, v[130:131]
	global_load_lds_dwordx4 v[6:7], off
	v_lshl_add_u64 v[6:7], v[42:43], 0, s[80:81]
	s_mov_b32 m0, s71
	s_add_u32 s42, s10, 0xb0080
	global_load_lds_dwordx4 v[6:7], off
	v_lshl_add_u64 v[6:7], v[48:49], 0, s[80:81]
	s_mov_b32 m0, s72
	s_addc_u32 s43, s11, 0
	global_load_lds_dwordx4 v[6:7], off
	v_lshl_add_u64 v[6:7], s[42:43], 0, v[146:147]
	s_add_i32 m0, s67, 0x1c000
	v_readlane_b32 s4, v250, 29
	global_load_lds_dwordx4 v[6:7], off
	v_lshl_add_u64 v[6:7], s[42:43], 0, v[128:129]
	s_add_i32 m0, s67, 0x1e000
	v_or_b32_e32 v162, s4, v134
	global_load_lds_dwordx4 v[6:7], off
	v_lshlrev_b32_e32 v141, 6, v162
	v_and_b32_e32 v170, 48, v139
	s_movk_i32 s4, 0x3c0
	v_and_or_b32 v141, v141, s4, v170
	v_and_b32_e32 v171, 0xfffffc00, v140
	v_readlane_b32 s4, v250, 27
	v_lshlrev_b32_e32 v173, 2, v162
	v_and_b32_e32 v173, 32, v173
	v_add_u32_e32 v172, s4, v171
	v_bitop3_b32 v172, v141, v172, v173 bitop3:0xde
	v_lshl_or_b32 v141, v134, 6, v170
	v_readlane_b32 s4, v250, 35
	v_lshlrev_b32_e32 v134, 2, v134
	v_and_b32_e32 v134, 32, v134
	v_add_u32_e32 v170, s4, v171
	s_movk_i32 s4, 0xb00
	v_bitop3_b32 v141, v141, v170, v134 bitop3:0xde
	v_lshrrev_b32_e32 v135, 1, v135
	v_mul_lo_u32 v134, v160, s4
	s_mov_b32 s8, 0xb000
	v_lshrrev_b32_e32 v160, 1, v136
	v_mul_lo_u32 v136, v137, s4
	v_mad_u64_u32 v[134:135], s[42:43], v135, s8, v[134:135]
	v_mad_u64_u32 v[136:137], s[42:43], v160, s8, v[136:137]
	s_waitcnt vmcnt(6)
	v_or_b32_e32 v134, v134, v161
	v_or_b32_e32 v136, v136, v142
	s_cmp_gt_i32 s5, 0
	v_add_lshl_u32 v134, v134, v163, 1
	v_mov_b32_e32 v135, v147
	s_mov_b64 s[44:45], 0xb0080
	v_add_lshl_u32 v136, v136, v143, 1
	v_mov_b32_e32 v137, v147
	v_readlane_b32 s8, v249, 35
	v_lshlrev_b32_e32 v124, 16, v60
	v_and_b32_e32 v125, 0xffff0000, v60
	v_lshlrev_b32_e32 v126, 16, v61
	v_and_b32_e32 v127, 0xffff0000, v61
	v_lshlrev_b32_e32 v120, 16, v62
	v_and_b32_e32 v121, 0xffff0000, v62
	v_lshlrev_b32_e32 v122, 16, v63
	v_and_b32_e32 v123, 0xffff0000, v63
	v_lshlrev_b32_e32 v108, 16, v52
	v_and_b32_e32 v109, 0xffff0000, v52
	v_lshlrev_b32_e32 v110, 16, v53
	v_and_b32_e32 v111, 0xffff0000, v53
	v_lshlrev_b32_e32 v104, 16, v54
	v_and_b32_e32 v105, 0xffff0000, v54
	v_lshlrev_b32_e32 v106, 16, v55
	v_and_b32_e32 v107, 0xffff0000, v55
	v_lshlrev_b32_e32 v96, 16, v50
	v_and_b32_e32 v97, 0xffff0000, v50
	v_lshlrev_b32_e32 v98, 16, v51
	v_and_b32_e32 v99, 0xffff0000, v51
	v_lshlrev_b32_e32 v80, 16, v32
	v_and_b32_e32 v81, 0xffff0000, v32
	v_lshlrev_b32_e32 v82, 16, v33
	v_and_b32_e32 v83, 0xffff0000, v33
	v_lshlrev_b32_e32 v76, 16, v34
	v_and_b32_e32 v77, 0xffff0000, v34
	v_lshlrev_b32_e32 v78, 16, v35
	v_and_b32_e32 v79, 0xffff0000, v35
	v_lshlrev_b32_e32 v68, 16, v28
	v_and_b32_e32 v69, 0xffff0000, v28
	v_lshlrev_b32_e32 v70, 16, v29
	v_and_b32_e32 v71, 0xffff0000, v29
	v_lshlrev_b32_e32 v64, 16, v30
	v_and_b32_e32 v65, 0xffff0000, v30
	v_lshlrev_b32_e32 v66, 16, v31
	v_and_b32_e32 v67, 0xffff0000, v31
	v_lshlrev_b32_e32 v28, 16, v12
	v_and_b32_e32 v29, 0xffff0000, v12
	v_lshlrev_b32_e32 v30, 16, v13
	v_and_b32_e32 v31, 0xffff0000, v13
	v_lshlrev_b32_e32 v12, 16, v14
	v_and_b32_e32 v13, 0xffff0000, v14
	v_lshlrev_b32_e32 v14, 16, v15
	v_and_b32_e32 v15, 0xffff0000, v15
	v_lshlrev_b32_e32 v32, 16, v4
	v_and_b32_e32 v33, 0xffff0000, v4
	v_lshlrev_b32_e32 v34, 16, v5
	v_and_b32_e32 v35, 0xffff0000, v5
	v_lshlrev_b32_e32 v4, 16, v36
	v_and_b32_e32 v5, 0xffff0000, v36
	v_lshlrev_b32_e32 v6, 16, v37
	v_and_b32_e32 v7, 0xffff0000, v37
	v_lshlrev_b32_e32 v52, 16, v38
	v_and_b32_e32 v53, 0xffff0000, v38
	v_lshlrev_b32_e32 v54, 16, v39
	v_and_b32_e32 v55, 0xffff0000, v39
	v_lshlrev_b32_e32 v60, 16, v24
	v_and_b32_e32 v61, 0xffff0000, v24
	v_lshlrev_b32_e32 v62, 16, v25
	v_and_b32_e32 v63, 0xffff0000, v25
	v_lshlrev_b32_e32 v48, 16, v26
	v_and_b32_e32 v49, 0xffff0000, v26
	v_lshlrev_b32_e32 v50, 16, v27
	v_and_b32_e32 v51, 0xffff0000, v27
	v_lshlrev_b32_e32 v36, 16, v20
	v_and_b32_e32 v37, 0xffff0000, v20
	v_lshlrev_b32_e32 v38, 16, v21
	v_and_b32_e32 v39, 0xffff0000, v21
	v_lshlrev_b32_e32 v20, 16, v22
	v_and_b32_e32 v21, 0xffff0000, v22
	v_lshlrev_b32_e32 v22, 16, v23
	v_and_b32_e32 v23, 0xffff0000, v23
	v_lshlrev_b32_e32 v40, 16, v8
	v_and_b32_e32 v41, 0xffff0000, v8
	v_lshlrev_b32_e32 v42, 16, v9
	v_and_b32_e32 v43, 0xffff0000, v9
	v_lshlrev_b32_e32 v24, 16, v10
	v_and_b32_e32 v25, 0xffff0000, v10
	v_lshlrev_b32_e32 v26, 16, v11
	v_and_b32_e32 v27, 0xffff0000, v11
	v_lshlrev_b32_e32 v8, 16, v0
	v_and_b32_e32 v9, 0xffff0000, v0
	v_lshlrev_b32_e32 v10, 16, v1
	v_and_b32_e32 v11, 0xffff0000, v1
	v_lshlrev_b32_e32 v0, 16, v2
	v_and_b32_e32 v1, 0xffff0000, v2
	v_lshlrev_b32_e32 v2, 16, v3
	v_and_b32_e32 v3, 0xffff0000, v3
	s_mov_b32 s74, 0
	s_cselect_b64 s[50:51], -1, 0
	s_add_i32 s73, s5, -2
	v_lshl_add_u64 v[134:135], v[134:135], 0, s[44:45]
	v_lshl_add_u64 v[136:137], v[136:137], 0, s[44:45]
	v_add_u32_e32 v142, 0, v172
	v_readlane_b32 s4, v248, 12
	s_mov_b32 s66, s8
	s_barrier
	v_readlane_b32 s9, v249, 36
	s_branch .LBB0_562

; #define PG8_LAS __attribute__((address_space(3)))
; __device__ __forceinline__ void tile_row_ss(const AccT& acc, PG8_LAS float* P, int wr, int wc, int fr, int fq) {
; #pragma unroll
;     for (int ai = 0; ai < 2; ++ai)
; #pragma unroll
;         for (int m = 0; m < 4; ++m) { float ss = 0.f;
; #pragma unroll
;             for (int bj = 0; bj < 2; ++bj) { const f32x4 v0 = acc[ai][bj][m][0], v1 = acc[ai][bj][m][1];
;                 ss += (v0[0] * v0[0] + v0[1] * v0[1]) + (v0[2] * v0[2] + v0[3] * v0[3]) + (v1[0] * v1[0] + v1[1] * v1[1]) + (v1[2] * v1[2] + v1[3] * v1[3]); }
;             ss += __shfl_xor(ss, 16); ss += __shfl_xor(ss, 32);
;             if (fq == 0) P[(ai * HALF + wr * 64 + m * 16 + fr) * 4 + wc] = ss; }
; }
.LBB0_580:
	v_mul_f32_e32 v130, v125, v125
	v_mul_f32_e32 v131, v127, v127
	v_fmac_f32_e32 v130, v124, v124
	v_fmac_f32_e32 v131, v126, v126
	v_add_f32_e32 v130, v130, v131
	v_mul_f32_e32 v131, v121, v121
	v_fmac_f32_e32 v131, v120, v120
	v_add_f32_e32 v130, v131, v130
	v_mul_f32_e32 v131, v123, v123
	v_fmac_f32_e32 v131, v122, v122
	v_add_f32_e32 v130, v131, v130
	v_mul_f32_e32 v131, v117, v117
	v_mul_f32_e32 v132, v119, v119
	v_fmac_f32_e32 v131, v116, v116
	v_fmac_f32_e32 v132, v118, v118
	v_add_f32_e32 v131, v131, v132
	v_mul_f32_e32 v132, v113, v113
	v_and_b32_e32 v129, 64, v168
	v_fmac_f32_e32 v132, v112, v112
	v_xor_b32_e32 v128, 16, v168
	v_add_u32_e32 v129, 64, v129
	v_add_f32_e32 v131, v132, v131
	v_mul_f32_e32 v132, v115, v115
	v_cmp_lt_i32_e32 vcc, v128, v129
	v_fmac_f32_e32 v132, v114, v114
	v_add_f32_e32 v131, v132, v131
	v_cndmask_b32_e32 v128, v168, v128, vcc
	v_lshlrev_b32_e32 v128, 2, v128
	v_add_f32_e32 v131, v131, v130
	ds_bpermute_b32 v132, v128, v131
	v_xor_b32_e32 v130, 32, v168
	v_cmp_lt_i32_e32 vcc, v130, v129
	v_readlane_b32 s5, v249, 19
	s_barrier
	v_cndmask_b32_e32 v129, v168, v130, vcc
	v_lshlrev_b32_e32 v130, 2, v129
	s_waitcnt lgkmcnt(0)
	v_add_f32_e32 v131, v131, v132
	v_mov_b32_e32 v132, v131
	s_nop 1
	v_permlane32_swap_b32_e32 v131, v132
	v_cmp_gt_u32_e32 vcc, 16, v139
	v_add_u32_e32 v129, s5, v140
	s_and_saveexec_b64 s[10:11], vcc
	v_readlane_b32 s68, v248, 18
	v_readlane_b32 s72, v250, 29
	v_readlane_b32 s69, v248, 19
	s_movk_i32 s67, 0x2000
	s_mov_b32 s52, 0x10000
	s_mov_b32 s73, 0x18000
	s_mov_b32 s70, 0x1a000
	s_mov_b32 s71, 0xa000
	s_mov_b32 s53, 0x1c000
	s_mov_b32 s74, 0x1e000
	s_mov_b32 s75, 0xc000
	s_mov_b32 s76, 0x38000
	s_cbranch_execz .LBB0_582
	s_waitcnt lgkmcnt(0)
	v_add_f32_e32 v131, v131, v132
	ds_write_b32 v129, v131
.LBB0_582:
	s_or_b64 exec, exec, s[10:11]
	v_mul_f32_e32 v131, v109, v109
	s_waitcnt lgkmcnt(0)
	v_mul_f32_e32 v132, v111, v111
	v_fmac_f32_e32 v131, v108, v108
	v_fmac_f32_e32 v132, v110, v110
	v_add_f32_e32 v131, v131, v132
	v_mul_f32_e32 v132, v105, v105
	v_fmac_f32_e32 v132, v104, v104
	v_add_f32_e32 v131, v132, v131
	v_mul_f32_e32 v132, v107, v107
	v_fmac_f32_e32 v132, v106, v106
	v_add_f32_e32 v131, v132, v131
	v_mul_f32_e32 v132, v101, v101
	v_mul_f32_e32 v133, v103, v103
	v_fmac_f32_e32 v132, v100, v100
	v_fmac_f32_e32 v133, v102, v102
	v_add_f32_e32 v132, v132, v133
	v_mul_f32_e32 v133, v97, v97
	v_fmac_f32_e32 v133, v96, v96
	v_add_f32_e32 v132, v133, v132
	v_mul_f32_e32 v133, v99, v99
	v_fmac_f32_e32 v133, v98, v98
	v_add_f32_e32 v132, v133, v132
	v_add_f32_e32 v131, v132, v131
	ds_bpermute_b32 v132, v128, v131
	s_waitcnt lgkmcnt(0)
	v_add_f32_e32 v131, v131, v132
	v_mov_b32_e32 v132, v131
	s_nop 1
	v_permlane32_swap_b32_e32 v131, v132
	s_and_saveexec_b64 s[10:11], vcc
	s_cbranch_execz .LBB0_584
	s_waitcnt lgkmcnt(0)
	v_add_f32_e32 v131, v131, v132
	ds_write_b32 v129, v131 offset:256
.LBB0_584:
	s_or_b64 exec, exec, s[10:11]
	v_mul_f32_e32 v131, v93, v93
	s_waitcnt lgkmcnt(0)
	v_mul_f32_e32 v132, v95, v95
	v_fmac_f32_e32 v131, v92, v92
	v_fmac_f32_e32 v132, v94, v94
	v_add_f32_e32 v131, v131, v132
	v_mul_f32_e32 v132, v89, v89
	v_fmac_f32_e32 v132, v88, v88
	v_add_f32_e32 v131, v132, v131
	v_mul_f32_e32 v132, v91, v91
	v_fmac_f32_e32 v132, v90, v90
	v_add_f32_e32 v131, v132, v131
	v_mul_f32_e32 v132, v85, v85
	v_mul_f32_e32 v133, v87, v87
	v_fmac_f32_e32 v132, v84, v84
	v_fmac_f32_e32 v133, v86, v86
	v_add_f32_e32 v132, v132, v133
	v_mul_f32_e32 v133, v73, v73
	v_fmac_f32_e32 v133, v72, v72
	v_add_f32_e32 v132, v133, v132
	v_mul_f32_e32 v133, v75, v75
	v_fmac_f32_e32 v133, v74, v74
	v_add_f32_e32 v132, v133, v132
	v_add_f32_e32 v131, v132, v131
	ds_bpermute_b32 v132, v128, v131
	s_waitcnt lgkmcnt(0)
	v_add_f32_e32 v131, v131, v132
	v_mov_b32_e32 v132, v131
	s_nop 1
	v_permlane32_swap_b32_e32 v131, v132
	s_and_saveexec_b64 s[10:11], vcc
	s_cbranch_execz .LBB0_586
	s_waitcnt lgkmcnt(0)
	v_add_f32_e32 v131, v131, v132
	ds_write_b32 v129, v131 offset:512
.LBB0_586:
	s_or_b64 exec, exec, s[10:11]
	v_mul_f32_e32 v131, v81, v81
	s_waitcnt lgkmcnt(0)
	v_mul_f32_e32 v132, v83, v83
	v_fmac_f32_e32 v131, v80, v80
	v_fmac_f32_e32 v132, v82, v82
	v_add_f32_e32 v131, v131, v132
	v_mul_f32_e32 v132, v77, v77
	v_fmac_f32_e32 v132, v76, v76
	v_add_f32_e32 v131, v132, v131
	v_mul_f32_e32 v132, v79, v79
	v_fmac_f32_e32 v132, v78, v78
	v_add_f32_e32 v131, v132, v131
	v_mul_f32_e32 v132, v69, v69
	v_mul_f32_e32 v133, v71, v71
	v_fmac_f32_e32 v132, v68, v68
	v_fmac_f32_e32 v133, v70, v70
	v_add_f32_e32 v132, v132, v133
	v_mul_f32_e32 v133, v65, v65
	v_fmac_f32_e32 v133, v64, v64
	v_add_f32_e32 v132, v133, v132
	v_mul_f32_e32 v133, v67, v67
	v_fmac_f32_e32 v133, v66, v66
	v_add_f32_e32 v132, v133, v132
	v_add_f32_e32 v131, v132, v131
	ds_bpermute_b32 v132, v128, v131
	s_waitcnt lgkmcnt(0)
	v_add_f32_e32 v131, v131, v132
	v_mov_b32_e32 v132, v131
	s_nop 1
	v_permlane32_swap_b32_e32 v131, v132
	s_and_saveexec_b64 s[10:11], vcc
	s_cbranch_execz .LBB0_588
	s_waitcnt lgkmcnt(0)
	v_add_f32_e32 v131, v131, v132
	ds_write_b32 v129, v131 offset:768
; __device__ __forceinline__ void tile_row_ss(const AccT& acc, PG8_LAS float* P, int wr, int wc, int fr, int fq) {
;     ...
;         for (int m = 0; m < 4; ++m) { float ss = 0.f;
; #pragma unroll
;             for (int bj = 0; bj < 2; ++bj) { const f32x4 v0 = acc[ai][bj][m][0], v1 = acc[ai][bj][m][1];
;                 ss += (v0[0] * v0[0] + v0[1] * v0[1]) + (v0[2] * v0[2] + v0[3] * v0[3]) + (v1[0] * v1[0] + v1[1] * v1[1]) + (v1[2] * v1[2] + v1[3] * v1[3]); }
;             ss += __shfl_xor(ss, 16); ss += __shfl_xor(ss, 32);
;             if (fq == 0) P[(ai * HALF + wr * 64 + m * 16 + fr) * 4 + wc] = ss; }
.LBB0_588:
	s_or_b64 exec, exec, s[10:11]
	v_mul_f32_e32 v131, v57, v57
	s_waitcnt lgkmcnt(0)
	v_mul_f32_e32 v132, v59, v59
	v_fmac_f32_e32 v131, v56, v56
	v_fmac_f32_e32 v132, v58, v58
	v_add_f32_e32 v131, v131, v132
	v_mul_f32_e32 v132, v45, v45
	v_fmac_f32_e32 v132, v44, v44
	v_add_f32_e32 v131, v132, v131
	v_mul_f32_e32 v132, v47, v47
	v_fmac_f32_e32 v132, v46, v46
	v_add_f32_e32 v131, v132, v131
	v_mul_f32_e32 v132, v29, v29
	v_mul_f32_e32 v133, v31, v31
	v_fmac_f32_e32 v132, v28, v28
	v_fmac_f32_e32 v133, v30, v30
	v_add_f32_e32 v132, v132, v133
	v_mul_f32_e32 v133, v13, v13
	v_fmac_f32_e32 v133, v12, v12
	v_add_f32_e32 v132, v133, v132
	v_mul_f32_e32 v133, v15, v15
	v_fmac_f32_e32 v133, v14, v14
	v_add_f32_e32 v132, v133, v132
	v_add_f32_e32 v131, v132, v131
	ds_bpermute_b32 v132, v128, v131
	s_waitcnt lgkmcnt(0)
	v_add_f32_e32 v131, v131, v132
	v_mov_b32_e32 v132, v131
	s_nop 1
	v_permlane32_swap_b32_e32 v131, v132
	s_and_saveexec_b64 s[10:11], vcc
	s_cbranch_execz .LBB0_590
	s_waitcnt lgkmcnt(0)
	v_add_f32_e32 v131, v131, v132
	ds_write_b32 v129, v131 offset:2048
.LBB0_590:
	s_or_b64 exec, exec, s[10:11]
	v_mul_f32_e32 v131, v33, v33
	s_waitcnt lgkmcnt(0)
	v_mul_f32_e32 v132, v35, v35
	v_fmac_f32_e32 v131, v32, v32
	v_fmac_f32_e32 v132, v34, v34
	v_add_f32_e32 v131, v131, v132
	v_mul_f32_e32 v132, v17, v17
	v_fmac_f32_e32 v132, v16, v16
	v_add_f32_e32 v131, v132, v131
	v_mul_f32_e32 v132, v19, v19
	v_fmac_f32_e32 v132, v18, v18
	v_add_f32_e32 v131, v132, v131
	v_mul_f32_e32 v132, v5, v5
	v_mul_f32_e32 v133, v7, v7
	v_fmac_f32_e32 v132, v4, v4
	v_fmac_f32_e32 v133, v6, v6
	v_add_f32_e32 v132, v132, v133
	v_mul_f32_e32 v133, v53, v53
	v_fmac_f32_e32 v133, v52, v52
	v_add_f32_e32 v132, v133, v132
	v_mul_f32_e32 v133, v55, v55
	v_fmac_f32_e32 v133, v54, v54
	v_add_f32_e32 v132, v133, v132
	v_add_f32_e32 v131, v132, v131
	ds_bpermute_b32 v132, v128, v131
	s_waitcnt lgkmcnt(0)
	v_add_f32_e32 v131, v131, v132
	v_mov_b32_e32 v132, v131
	s_nop 1
	v_permlane32_swap_b32_e32 v131, v132
	s_and_saveexec_b64 s[10:11], vcc
	s_cbranch_execz .LBB0_592
	s_waitcnt lgkmcnt(0)
	v_add_f32_e32 v131, v131, v132
	ds_write_b32 v129, v131 offset:2304
.LBB0_592:
	s_or_b64 exec, exec, s[10:11]
	v_mul_f32_e32 v131, v61, v61
	s_waitcnt lgkmcnt(0)
	v_mul_f32_e32 v132, v63, v63
	v_fmac_f32_e32 v131, v60, v60
	v_fmac_f32_e32 v132, v62, v62
	v_add_f32_e32 v131, v131, v132
	v_mul_f32_e32 v132, v49, v49
	v_fmac_f32_e32 v132, v48, v48
	v_add_f32_e32 v131, v132, v131
	v_mul_f32_e32 v132, v51, v51
	v_fmac_f32_e32 v132, v50, v50
	v_add_f32_e32 v131, v132, v131
	v_mul_f32_e32 v132, v37, v37
	v_mul_f32_e32 v133, v39, v39
	v_fmac_f32_e32 v132, v36, v36
	v_fmac_f32_e32 v133, v38, v38
	v_add_f32_e32 v132, v132, v133
	v_mul_f32_e32 v133, v21, v21
	v_fmac_f32_e32 v133, v20, v20
	v_add_f32_e32 v132, v133, v132
	v_mul_f32_e32 v133, v23, v23
	v_fmac_f32_e32 v133, v22, v22
	v_add_f32_e32 v132, v133, v132
	v_add_f32_e32 v131, v132, v131
	ds_bpermute_b32 v132, v128, v131
	s_waitcnt lgkmcnt(0)
	v_add_f32_e32 v131, v131, v132
	v_mov_b32_e32 v132, v131
	s_nop 1
	v_permlane32_swap_b32_e32 v131, v132
	s_and_saveexec_b64 s[10:11], vcc
	s_cbranch_execz .LBB0_594
	s_waitcnt lgkmcnt(0)
	v_add_f32_e32 v131, v131, v132
	ds_write_b32 v129, v131 offset:2560
.LBB0_594:
	s_or_b64 exec, exec, s[10:11]
	v_mul_f32_e32 v131, v41, v41
	s_waitcnt lgkmcnt(0)
	v_mul_f32_e32 v132, v43, v43
	v_fmac_f32_e32 v131, v40, v40
	v_fmac_f32_e32 v132, v42, v42
	v_add_f32_e32 v131, v131, v132
	v_mul_f32_e32 v132, v25, v25
	v_fmac_f32_e32 v132, v24, v24
	v_add_f32_e32 v131, v132, v131
	v_mul_f32_e32 v132, v27, v27
	v_fmac_f32_e32 v132, v26, v26
	v_add_f32_e32 v131, v132, v131
	v_mul_f32_e32 v132, v9, v9
	v_mul_f32_e32 v133, v11, v11
	v_fmac_f32_e32 v132, v8, v8
	v_fmac_f32_e32 v133, v10, v10
	v_add_f32_e32 v132, v132, v133
	v_mul_f32_e32 v133, v1, v1
	v_fmac_f32_e32 v133, v0, v0
	v_add_f32_e32 v132, v133, v132
	v_mul_f32_e32 v133, v3, v3
	v_fmac_f32_e32 v133, v2, v2
	v_add_f32_e32 v132, v133, v132
	v_add_f32_e32 v131, v132, v131
	ds_bpermute_b32 v128, v128, v131
	s_waitcnt lgkmcnt(0)
	v_add_f32_e32 v128, v131, v128
	v_mov_b32_e32 v130, v128
	s_nop 1
	v_permlane32_swap_b32_e32 v128, v130
	s_and_saveexec_b64 s[10:11], vcc
	s_cbranch_execz .LBB0_596
	s_waitcnt lgkmcnt(0)
	v_add_f32_e32 v128, v128, v130
	ds_write_b32 v129, v128 offset:2816

; __device__ __forceinline__ float bf_lo(unsigned w) { return __uint_as_float(w << 16); }
; __device__ __forceinline__ float bf_hi(unsigned w) { return __uint_as_float(w & 0xffff0000u); }
; #define PG8_STAGE(bufoff, gbase, voff) do { _Pragma("unroll") for (int _i = 0; _i < 2; ++_i) \
;         __builtin_amdgcn_global_load_lds((const unsigned*)((const char*)(gbase) + (voff)[_i]), (PG8_LAS unsigned*)(lds + (bufoff) + ldsw + _i * 8192), 16, 0, 0); } while (0)
; #define PG8_WAIT_V(n) asm volatile("s_waitcnt vmcnt(" #n ")" ::: "memory")
; #define PG8_BAR __builtin_amdgcn_s_barrier()
; __device__ __forceinline__ void acc_from_xb(AccT& acc, const bf16_t* xb, const Unit& u, int wr, int wc, int fr, int fq) {
;     const unsigned off0 = (unsigned)(u.pm * BM + wr * 64 + fr) * DM + u.pn * BM + wc * 32 + 8 * fq;
; #pragma unroll
;     for (int ai = 0; ai < 2; ++ai)
; #pragma unroll
;         for (int m = 0; m < 4; ++m)
; #pragma unroll
;             for (int bj = 0; bj < 2; ++bj) { const u32x4 w = *(const u32x4*)(xb + off0 + (unsigned)(ai * HALF + m * 16) * DM + bj * HALF);
;                 acc[ai][bj][m][0] = (f32x4){bf_lo(w.x), bf_hi(w.x), bf_lo(w.y), bf_hi(w.y)}; acc[ai][bj][m][1] = (f32x4){bf_lo(w.z), bf_hi(w.z), bf_lo(w.w), bf_hi(w.w)}; }
; template <class Epi, class Sched, bool ALIGN_EPI = false, bool SP2 = false>
; __device__ __forceinline__ void gemm_phase(PG8_LAS unsigned char* lds, const Gemm g, const Sched& S, const Epi& E, const int wid) {
;     ...
;     if constexpr (SP2) {
;         PG8_STAGE(PG8_SB(0, 0), cB, voffB); PG8_STAGE(PG8_SB(0, 1), cB + hstepB, voffB); PG8_STAGE(PG8_SA(0, 0), cA, voffA); PG8_STAGE(PG8_SA(0, 1), cA + hstepA, voffA);
;         if (wr == 1) PG8_BAR;
;         PG8_WAIT_V(2); PG8_BAR;
;         PG8_STAGE(PG8_SB(1, 0), cB + kstep, voffB); PG8_STAGE(PG8_SA(1, 0), cA + kstep, voffA); PG8_STAGE(PG8_SB(1, 1), cB + hstepB + kstep, voffB);
;         PG8_WAIT_V(6); PG8_BAR;
.LBB0_615:
	s_waitcnt vmcnt(8)
	v_lshlrev_b32_e32 v96, 16, v48
	v_and_b32_e32 v97, 0xffff0000, v48
	v_lshlrev_b32_e32 v98, 16, v49
	v_and_b32_e32 v99, 0xffff0000, v49
	v_lshlrev_b32_e32 v88, 16, v50
	v_and_b32_e32 v89, 0xffff0000, v50
	v_lshlrev_b32_e32 v90, 16, v51
	v_and_b32_e32 v91, 0xffff0000, v51
	v_lshlrev_b32_e32 v100, 16, v44
	v_and_b32_e32 v101, 0xffff0000, v44
	v_lshlrev_b32_e32 v102, 16, v45
	v_and_b32_e32 v103, 0xffff0000, v45
	v_lshlrev_b32_e32 v92, 16, v46
	v_and_b32_e32 v93, 0xffff0000, v46
	v_lshlrev_b32_e32 v94, 16, v47
	v_and_b32_e32 v95, 0xffff0000, v47
	v_lshlrev_b32_e32 v48, 16, v16
	v_and_b32_e32 v49, 0xffff0000, v16
	v_lshlrev_b32_e32 v50, 16, v17
	v_and_b32_e32 v51, 0xffff0000, v17
	v_lshlrev_b32_e32 v44, 16, v18
	v_and_b32_e32 v45, 0xffff0000, v18
	v_lshlrev_b32_e32 v46, 16, v19
	v_and_b32_e32 v47, 0xffff0000, v19
	v_lshlrev_b32_e32 v16, 16, v2
	v_and_b32_e32 v17, 0xffff0000, v2
	v_lshlrev_b32_e32 v18, 16, v3
	v_and_b32_e32 v19, 0xffff0000, v3
	v_lshl_add_u64 v[2:3], s[10:11], 0, v[146:147]
	v_mov_b32_e32 v129, v147
	v_readlane_b32 s52, v249, 31
	v_lshlrev_b32_e32 v80, 16, v40
	v_and_b32_e32 v81, 0xffff0000, v40
	v_lshlrev_b32_e32 v82, 16, v41
	v_and_b32_e32 v83, 0xffff0000, v41
	v_lshl_add_u64 v[40:41], s[10:11], 0, v[128:129]
	v_mov_b32_e32 v133, v147
	v_readlane_b32 s53, v249, 32
	v_lshl_add_u64 v[2:3], v[2:3], 0, s[80:81]
	s_add_i32 m0, s66, 0x18000
	v_lshlrev_b32_e32 v72, 16, v42
	v_and_b32_e32 v73, 0xffff0000, v42
	v_lshlrev_b32_e32 v74, 16, v43
	v_and_b32_e32 v75, 0xffff0000, v43
	v_lshl_add_u64 v[42:43], s[52:53], 0, v[132:133]
	v_mov_b32_e32 v131, v147
	s_waitcnt vmcnt(2)
	s_barrier
	global_load_lds_dwordx4 v[2:3], off
	v_lshl_add_u64 v[2:3], v[40:41], 0, s[80:81]
	s_add_i32 m0, s66, 0x1a000
	s_add_i32 s71, s66, 0x8000
	s_add_i32 s72, s66, 0xa000
	v_lshlrev_b32_e32 v108, 16, v52
	v_and_b32_e32 v109, 0xffff0000, v52
	v_lshlrev_b32_e32 v110, 16, v53
	v_and_b32_e32 v111, 0xffff0000, v53
	v_lshl_add_u64 v[52:53], s[52:53], 0, v[130:131]
	global_load_lds_dwordx4 v[2:3], off
	v_lshl_add_u64 v[2:3], v[42:43], 0, s[80:81]
	s_mov_b32 m0, s71
	s_add_u32 s42, s10, 0xb0080
	global_load_lds_dwordx4 v[2:3], off
	v_lshl_add_u64 v[2:3], v[52:53], 0, s[80:81]
	s_mov_b32 m0, s72
	s_addc_u32 s43, s11, 0
	global_load_lds_dwordx4 v[2:3], off
	v_lshl_add_u64 v[2:3], s[42:43], 0, v[146:147]
	s_add_i32 m0, s66, 0x1c000
	v_readlane_b32 s4, v250, 29
	global_load_lds_dwordx4 v[2:3], off
	v_lshl_add_u64 v[2:3], s[42:43], 0, v[128:129]
	s_add_i32 m0, s66, 0x1e000
	v_or_b32_e32 v142, s4, v140
	global_load_lds_dwordx4 v[2:3], off
	v_lshlrev_b32_e32 v163, 6, v142
	v_and_b32_e32 v170, 48, v138
	s_movk_i32 s4, 0x3c0
	v_and_or_b32 v163, v163, s4, v170
	v_and_b32_e32 v171, 0xfffffc00, v139
	v_readlane_b32 s4, v250, 27
	v_lshlrev_b32_e32 v142, 2, v142
	v_and_b32_e32 v142, 32, v142
	v_add_u32_e32 v172, s4, v171
	v_readlane_b32 s4, v250, 35
	v_bitop3_b32 v163, v163, v172, v142 bitop3:0xde
	v_lshl_or_b32 v142, v140, 6, v170
	v_add_u32_e32 v170, s4, v171
	v_lshlrev_b32_e32 v171, 2, v140
	v_and_b32_e32 v171, 32, v171
	s_movk_i32 s4, 0xb00
	v_bitop3_b32 v142, v142, v170, v171 bitop3:0xde
	v_lshrrev_b32_e32 v170, 1, v134
	v_mul_lo_u32 v134, v135, s4
	s_mov_b32 s8, 0xb000
	v_mad_u64_u32 v[134:135], s[42:43], v170, s8, v[134:135]
	v_or_b32_e32 v134, v134, v161
	v_lshrrev_b32_e32 v161, 1, v136
	v_mul_lo_u32 v136, v137, s4
	v_mad_u64_u32 v[136:137], s[42:43], v161, s8, v[136:137]
	s_waitcnt vmcnt(6)
	v_or_b32_e32 v136, v136, v143
	s_cmp_gt_i32 s5, 0
	v_add_lshl_u32 v134, v134, v162, 1
	v_mov_b32_e32 v135, v147
	s_mov_b64 s[44:45], 0xb0080
	v_add_lshl_u32 v136, v136, v160, 1
	v_mov_b32_e32 v137, v147
	v_readlane_b32 s8, v249, 35
	v_lshlrev_b32_e32 v124, 16, v60
	v_and_b32_e32 v125, 0xffff0000, v60
	v_lshlrev_b32_e32 v126, 16, v61
	v_and_b32_e32 v127, 0xffff0000, v61
	v_lshlrev_b32_e32 v120, 16, v62
	v_and_b32_e32 v121, 0xffff0000, v62
	v_lshlrev_b32_e32 v122, 16, v63
	v_and_b32_e32 v123, 0xffff0000, v63
	v_lshlrev_b32_e32 v116, 16, v56
	v_and_b32_e32 v117, 0xffff0000, v56
	v_lshlrev_b32_e32 v118, 16, v57
	v_and_b32_e32 v119, 0xffff0000, v57
	v_lshlrev_b32_e32 v112, 16, v58
	v_and_b32_e32 v113, 0xffff0000, v58
	v_lshlrev_b32_e32 v114, 16, v59
	v_and_b32_e32 v115, 0xffff0000, v59
	v_lshlrev_b32_e32 v104, 16, v54
	v_and_b32_e32 v105, 0xffff0000, v54
	v_lshlrev_b32_e32 v106, 16, v55
	v_and_b32_e32 v107, 0xffff0000, v55
	v_lshlrev_b32_e32 v84, 16, v24
	v_and_b32_e32 v85, 0xffff0000, v24
	v_lshlrev_b32_e32 v86, 16, v25
	v_and_b32_e32 v87, 0xffff0000, v25
	v_lshlrev_b32_e32 v76, 16, v26
	v_and_b32_e32 v77, 0xffff0000, v26
	v_lshlrev_b32_e32 v78, 16, v27
	v_and_b32_e32 v79, 0xffff0000, v27
	v_lshlrev_b32_e32 v68, 16, v20
	v_and_b32_e32 v69, 0xffff0000, v20
	v_lshlrev_b32_e32 v70, 16, v21
	v_and_b32_e32 v71, 0xffff0000, v21
	v_lshlrev_b32_e32 v60, 16, v22
	v_and_b32_e32 v61, 0xffff0000, v22
	v_lshlrev_b32_e32 v62, 16, v23
	v_and_b32_e32 v63, 0xffff0000, v23
	v_lshlrev_b32_e32 v20, 16, v12
	v_and_b32_e32 v21, 0xffff0000, v12
	v_lshlrev_b32_e32 v22, 16, v13
	v_and_b32_e32 v23, 0xffff0000, v13
	v_lshlrev_b32_e32 v12, 16, v14
	v_and_b32_e32 v13, 0xffff0000, v14
	v_lshlrev_b32_e32 v14, 16, v15
	v_and_b32_e32 v15, 0xffff0000, v15
	v_lshlrev_b32_e32 v24, 16, v0
	v_and_b32_e32 v25, 0xffff0000, v0
	v_lshlrev_b32_e32 v26, 16, v1
	v_and_b32_e32 v27, 0xffff0000, v1
	v_lshlrev_b32_e32 v0, 16, v36
	v_and_b32_e32 v1, 0xffff0000, v36
	v_lshlrev_b32_e32 v2, 16, v37
	v_and_b32_e32 v3, 0xffff0000, v37
	v_lshlrev_b32_e32 v52, 16, v38
	v_and_b32_e32 v53, 0xffff0000, v38
	v_lshlrev_b32_e32 v54, 16, v39
	v_and_b32_e32 v55, 0xffff0000, v39
	v_lshlrev_b32_e32 v64, 16, v32
	v_and_b32_e32 v65, 0xffff0000, v32
	v_lshlrev_b32_e32 v66, 16, v33
	v_and_b32_e32 v67, 0xffff0000, v33
	v_lshlrev_b32_e32 v56, 16, v34
	v_and_b32_e32 v57, 0xffff0000, v34
	v_lshlrev_b32_e32 v58, 16, v35
	v_and_b32_e32 v59, 0xffff0000, v35
	v_lshlrev_b32_e32 v36, 16, v28
	v_and_b32_e32 v37, 0xffff0000, v28
	v_lshlrev_b32_e32 v38, 16, v29
	v_and_b32_e32 v39, 0xffff0000, v29
	v_lshlrev_b32_e32 v28, 16, v30
	v_and_b32_e32 v29, 0xffff0000, v30
	v_lshlrev_b32_e32 v30, 16, v31
	v_and_b32_e32 v31, 0xffff0000, v31
	v_lshlrev_b32_e32 v40, 16, v8
	v_and_b32_e32 v41, 0xffff0000, v8
	v_lshlrev_b32_e32 v42, 16, v9
	v_and_b32_e32 v43, 0xffff0000, v9
	v_lshlrev_b32_e32 v32, 16, v10
	v_and_b32_e32 v33, 0xffff0000, v10
	v_lshlrev_b32_e32 v34, 16, v11
	v_and_b32_e32 v35, 0xffff0000, v11
	v_lshlrev_b32_e32 v8, 16, v4
	v_and_b32_e32 v9, 0xffff0000, v4
	v_lshlrev_b32_e32 v10, 16, v5
	v_and_b32_e32 v11, 0xffff0000, v5
	v_lshlrev_b32_e32 v4, 16, v6
	v_and_b32_e32 v5, 0xffff0000, v6
	v_lshlrev_b32_e32 v6, 16, v7
	v_and_b32_e32 v7, 0xffff0000, v7
	s_mov_b32 s74, 0
	s_cselect_b64 s[50:51], -1, 0
	s_add_i32 s73, s5, -2
	v_lshl_add_u64 v[134:135], v[134:135], 0, s[44:45]
	v_lshl_add_u64 v[136:137], v[136:137], 0, s[44:45]
	v_add_u32_e32 v143, 0, v163
	v_readlane_b32 s4, v248, 12
	s_mov_b32 s70, s8
	s_barrier
	v_readlane_b32 s9, v249, 36
	s_branch .LBB0_617

; __device__ __forceinline__ unsigned pk_bf16(float lo, float hi) { f32x2 v = {lo, hi}; return __builtin_bit_cast(unsigned, __builtin_convertvector(v, bf16v2)); }
; __device__ __forceinline__ void tile_row_ss(const AccT& acc, PG8_LAS float* P, int wr, int wc, int fr, int fq) {
;     ...
;         for (int m = 0; m < 4; ++m) { float ss = 0.f;
; #pragma unroll
;             for (int bj = 0; bj < 2; ++bj) { const f32x4 v0 = acc[ai][bj][m][0], v1 = acc[ai][bj][m][1];
;                 ss += (v0[0] * v0[0] + v0[1] * v0[1]) + (v0[2] * v0[2] + v0[3] * v0[3]) + (v1[0] * v1[0] + v1[1] * v1[1]) + (v1[2] * v1[2] + v1[3] * v1[3]); }
;             ss += __shfl_xor(ss, 16); ss += __shfl_xor(ss, 32);
;             if (fq == 0) P[(ai * HALF + wr * 64 + m * 16 + fr) * 4 + wc] = ss; }
;     __device__ __forceinline__ void fused(AccT& acc, const Unit& u, int wr, int wc, int fr, int fq, PG8_LAS unsigned char* lds, int wid, int lane) const {
;     ...
;                 for (int bj = 0; bj < 2; ++bj) { const f32x4 v0 = acc[ai][bj][m][0], v1 = acc[ai][bj][m][1];
;                     u32x4 w; w.x = pk_bf16(v0[0], v0[1]); w.y = pk_bf16(v0[2], v0[3]); w.z = pk_bf16(v1[0], v1[1]); w.w = pk_bf16(v1[2], v1[3]);
;                     *(u32x4*)(xb + off0 + (unsigned)(ai * HALF + m * 16) * DM + bj * HALF) = w; }
;         tile_row_ss(acc, P, wr, wc, fr, fq);
.LBB0_635:
	s_lshl_b32 s5, s70, 8
	v_readlane_b32 s72, v250, 29
	s_add_i32 s8, s5, s72
	v_or_b32_e32 v128, s8, v140
	v_lshlrev_b32_e32 v128, 10, v128
	s_lshl_b32 s8, s4, 8
	v_add3_u32 v146, s8, v141, v128
	v_cvt_pk_bf16_f32 v128, v124, v125
	v_cvt_pk_bf16_f32 v129, v126, v127
	v_cvt_pk_bf16_f32 v130, v120, v121
	v_cvt_pk_bf16_f32 v131, v122, v123
	v_lshl_add_u64 v[132:133], v[146:147], 1, s[94:95]
	s_barrier
	global_store_dwordx4 v[132:133], v[128:131], off sc1
	v_add_co_u32_e32 v134, vcc, s39, v132
	s_nop 0
	v_cvt_pk_bf16_f32 v128, v116, v117
	v_cvt_pk_bf16_f32 v129, v118, v119
	v_cvt_pk_bf16_f32 v130, v112, v113
	v_cvt_pk_bf16_f32 v131, v114, v115
	global_store_dwordx4 v[132:133], v[128:131], off offset:256 sc1
	v_addc_co_u32_e32 v135, vcc, 0, v133, vcc
	s_nop 0
	v_cvt_pk_bf16_f32 v128, v108, v109
	v_cvt_pk_bf16_f32 v129, v110, v111
	v_cvt_pk_bf16_f32 v130, v104, v105
	v_cvt_pk_bf16_f32 v131, v106, v107
	global_store_dwordx4 v[134:135], v[128:131], off sc1
	s_mov_b32 s52, 0x10000
	s_mov_b32 s73, 0x18000
	v_cvt_pk_bf16_f32 v128, v96, v97
	v_cvt_pk_bf16_f32 v129, v98, v99
	v_cvt_pk_bf16_f32 v130, v88, v89
	v_cvt_pk_bf16_f32 v131, v90, v91
	global_store_dwordx4 v[134:135], v[128:131], off offset:256 sc1
	v_add_co_u32_e32 v134, vcc, s52, v132
	s_nop 0
	v_cvt_pk_bf16_f32 v128, v100, v101
	v_cvt_pk_bf16_f32 v129, v102, v103
	v_cvt_pk_bf16_f32 v130, v92, v93
	v_cvt_pk_bf16_f32 v131, v94, v95
	v_addc_co_u32_e32 v135, vcc, 0, v133, vcc
	global_store_dwordx4 v[134:135], v[128:131], off sc1
	s_mov_b32 s8, 0x40000
	v_mul_f32_e32 v125, v125, v125
	v_cvt_pk_bf16_f32 v128, v80, v81
	v_cvt_pk_bf16_f32 v129, v82, v83
	v_cvt_pk_bf16_f32 v130, v72, v73
	v_cvt_pk_bf16_f32 v131, v74, v75
	global_store_dwordx4 v[134:135], v[128:131], off offset:256 sc1
	v_add_co_u32_e32 v134, vcc, s73, v132
	s_nop 0
	v_cvt_pk_bf16_f32 v128, v84, v85
	v_cvt_pk_bf16_f32 v129, v86, v87
	v_cvt_pk_bf16_f32 v130, v76, v77
	v_cvt_pk_bf16_f32 v131, v78, v79
	v_addc_co_u32_e32 v135, vcc, 0, v133, vcc
	global_store_dwordx4 v[134:135], v[128:131], off sc1
	v_mul_f32_e32 v117, v117, v117
	v_fmac_f32_e32 v125, v124, v124
	v_cvt_pk_bf16_f32 v128, v68, v69
	v_cvt_pk_bf16_f32 v129, v70, v71
	v_cvt_pk_bf16_f32 v130, v60, v61
	v_cvt_pk_bf16_f32 v131, v62, v63
	global_store_dwordx4 v[134:135], v[128:131], off offset:256 sc1
	v_add_co_u32_e32 v134, vcc, s8, v132
	s_nop 0
	v_cvt_pk_bf16_f32 v128, v48, v49
	v_cvt_pk_bf16_f32 v129, v50, v51
	v_cvt_pk_bf16_f32 v130, v44, v45
	v_cvt_pk_bf16_f32 v131, v46, v47
	v_addc_co_u32_e32 v135, vcc, 0, v133, vcc
	global_store_dwordx4 v[134:135], v[128:131], off sc1
	s_mov_b32 s8, 0x48000
	v_mul_f32_e32 v124, v127, v127
	v_cvt_pk_bf16_f32 v128, v20, v21
	v_cvt_pk_bf16_f32 v129, v22, v23
	v_cvt_pk_bf16_f32 v130, v12, v13
	v_cvt_pk_bf16_f32 v131, v14, v15
	global_store_dwordx4 v[134:135], v[128:131], off offset:256 sc1
	v_add_co_u32_e32 v134, vcc, s8, v132
	s_nop 0
	v_cvt_pk_bf16_f32 v128, v24, v25
	v_cvt_pk_bf16_f32 v129, v26, v27
	v_cvt_pk_bf16_f32 v130, v16, v17
	v_cvt_pk_bf16_f32 v131, v18, v19
	v_addc_co_u32_e32 v135, vcc, 0, v133, vcc
	global_store_dwordx4 v[134:135], v[128:131], off sc1
	s_mov_b32 s8, 0x50000
	v_fmac_f32_e32 v117, v116, v116
	v_cvt_pk_bf16_f32 v128, v0, v1
	v_cvt_pk_bf16_f32 v129, v2, v3
	v_cvt_pk_bf16_f32 v130, v52, v53
	v_cvt_pk_bf16_f32 v131, v54, v55
	global_store_dwordx4 v[134:135], v[128:131], off offset:256 sc1
	v_add_co_u32_e32 v134, vcc, s8, v132
	s_nop 0
	v_cvt_pk_bf16_f32 v128, v64, v65
	v_cvt_pk_bf16_f32 v129, v66, v67
	v_cvt_pk_bf16_f32 v130, v56, v57
	v_cvt_pk_bf16_f32 v131, v58, v59
	v_addc_co_u32_e32 v135, vcc, 0, v133, vcc
	global_store_dwordx4 v[134:135], v[128:131], off sc1
	s_mov_b32 s8, 0x58000
	v_mul_f32_e32 v116, v119, v119
	v_cvt_pk_bf16_f32 v128, v36, v37
	v_cvt_pk_bf16_f32 v129, v38, v39
	v_cvt_pk_bf16_f32 v130, v28, v29
	v_cvt_pk_bf16_f32 v131, v30, v31
	global_store_dwordx4 v[134:135], v[128:131], off offset:256 sc1
	v_add_co_u32_e32 v134, vcc, s8, v132
	s_nop 0
	v_cvt_pk_bf16_f32 v128, v40, v41
	v_cvt_pk_bf16_f32 v129, v42, v43
	v_cvt_pk_bf16_f32 v130, v32, v33
	v_cvt_pk_bf16_f32 v131, v34, v35
	v_addc_co_u32_e32 v135, vcc, 0, v133, vcc
	v_fmac_f32_e32 v124, v126, v126
	v_mul_f32_e32 v121, v121, v121
	v_fmac_f32_e32 v116, v118, v118
	v_mul_f32_e32 v113, v113, v113
	global_store_dwordx4 v[134:135], v[128:131], off sc1
	v_add_f32_e32 v124, v125, v124
	v_fmac_f32_e32 v121, v120, v120
	v_and_b32_e32 v129, 64, v168
	v_add_f32_e32 v116, v117, v116
	v_fmac_f32_e32 v113, v112, v112
	v_xor_b32_e32 v128, 16, v168
	v_add_u32_e32 v129, 64, v129
	v_add_f32_e32 v120, v121, v124
	v_mul_f32_e32 v121, v123, v123
	v_add_f32_e32 v112, v113, v116
	v_mul_f32_e32 v113, v115, v115
	v_cmp_lt_i32_e32 vcc, v128, v129
	v_fmac_f32_e32 v121, v122, v122
	v_fmac_f32_e32 v113, v114, v114
	v_cndmask_b32_e32 v128, v168, v128, vcc
	v_add_f32_e32 v120, v121, v120
	v_add_f32_e32 v112, v113, v112
	v_lshlrev_b32_e32 v128, 2, v128
	v_add_f32_e32 v112, v112, v120
	ds_bpermute_b32 v114, v128, v112
	v_xor_b32_e32 v113, 32, v168
	v_cmp_lt_i32_e32 vcc, v113, v129
	v_readlane_b32 s8, v249, 19
	v_cvt_pk_bf16_f32 v130, v8, v9
	v_cndmask_b32_e32 v113, v168, v113, vcc
	v_lshlrev_b32_e32 v113, 2, v113
	s_waitcnt lgkmcnt(0)
	v_add_f32_e32 v114, v112, v114
	v_mov_b32_e32 v115, v114
	s_nop 1
	v_permlane32_swap_b32_e32 v114, v115
	v_cvt_pk_bf16_f32 v131, v10, v11
	v_cvt_pk_bf16_f32 v132, v4, v5
	v_cvt_pk_bf16_f32 v133, v6, v7
	v_cmp_gt_u32_e32 vcc, 16, v138
	v_add_u32_e32 v112, s8, v139
	global_store_dwordx4 v[134:135], v[130:133], off offset:256 sc1
	s_and_saveexec_b64 s[10:11], vcc
	v_readlane_b32 s68, v248, 18
	v_readlane_b32 s69, v248, 19
	s_mov_b32 s66, 0x20000
	s_movk_i32 s67, 0x2000
	s_movk_i32 s50, 0x6000
	s_mov_b32 s71, 0xa000
	s_mov_b32 s53, 0x1c000
	s_mov_b32 s74, 0x1e000
	s_mov_b32 s75, 0xc000
	s_mov_b32 s51, 0x2e000
	s_mov_b32 s76, 0x38000
	s_cbranch_execz .LBB0_637
	s_waitcnt lgkmcnt(0)
	v_add_f32_e32 v114, v114, v115
	ds_write_b32 v112, v114
; __device__ __forceinline__ void tile_row_ss(const AccT& acc, PG8_LAS float* P, int wr, int wc, int fr, int fq) {
;     ...
;         for (int m = 0; m < 4; ++m) { float ss = 0.f;
; #pragma unroll
;             for (int bj = 0; bj < 2; ++bj) { const f32x4 v0 = acc[ai][bj][m][0], v1 = acc[ai][bj][m][1];
;                 ss += (v0[0] * v0[0] + v0[1] * v0[1]) + (v0[2] * v0[2] + v0[3] * v0[3]) + (v1[0] * v1[0] + v1[1] * v1[1]) + (v1[2] * v1[2] + v1[3] * v1[3]); }
;             ss += __shfl_xor(ss, 16); ss += __shfl_xor(ss, 32);
;             if (fq == 0) P[(ai * HALF + wr * 64 + m * 16 + fr) * 4 + wc] = ss; }
.LBB0_637:
	s_or_b64 exec, exec, s[10:11]
	v_mul_f32_e32 v109, v109, v109
	v_mul_f32_e32 v97, v97, v97
	v_fmac_f32_e32 v109, v108, v108
	v_mul_f32_e32 v108, v111, v111
	v_fmac_f32_e32 v97, v96, v96
	v_mul_f32_e32 v96, v99, v99
	v_fmac_f32_e32 v108, v110, v110
	v_mul_f32_e32 v105, v105, v105
	v_fmac_f32_e32 v96, v98, v98
	v_mul_f32_e32 v89, v89, v89
	v_add_f32_e32 v108, v109, v108
	v_fmac_f32_e32 v105, v104, v104
	v_add_f32_e32 v96, v97, v96
	v_fmac_f32_e32 v89, v88, v88
	v_add_f32_e32 v104, v105, v108
	v_mul_f32_e32 v105, v107, v107
	v_add_f32_e32 v88, v89, v96
	v_mul_f32_e32 v89, v91, v91
	v_fmac_f32_e32 v105, v106, v106
	v_fmac_f32_e32 v89, v90, v90
	v_add_f32_e32 v104, v105, v104
	v_add_f32_e32 v88, v89, v88
	v_add_f32_e32 v88, v88, v104
	ds_bpermute_b32 v89, v128, v88
	s_waitcnt lgkmcnt(0)
	v_add_f32_e32 v88, v88, v89
	v_mov_b32_e32 v89, v88
	s_nop 1
	v_permlane32_swap_b32_e32 v88, v89
	s_and_saveexec_b64 s[10:11], vcc
	s_mov_b32 s70, 0x1a000
	s_cbranch_execz .LBB0_639
	s_waitcnt lgkmcnt(0)
	v_add_f32_e32 v88, v88, v89
	ds_write_b32 v112, v88 offset:256
.LBB0_639:
	s_or_b64 exec, exec, s[10:11]
	v_mul_f32_e32 v88, v101, v101
	s_waitcnt lgkmcnt(0)
	v_mul_f32_e32 v89, v103, v103
	v_mul_f32_e32 v81, v81, v81
	v_fmac_f32_e32 v88, v100, v100
	v_fmac_f32_e32 v89, v102, v102
	v_fmac_f32_e32 v81, v80, v80
	v_mul_f32_e32 v80, v83, v83
	v_add_f32_e32 v88, v88, v89
	v_mul_f32_e32 v89, v93, v93
	v_fmac_f32_e32 v80, v82, v82
	v_mul_f32_e32 v73, v73, v73
	v_fmac_f32_e32 v89, v92, v92
	v_add_f32_e32 v80, v81, v80
	v_fmac_f32_e32 v73, v72, v72
	v_add_f32_e32 v88, v89, v88
	v_mul_f32_e32 v89, v95, v95
	v_add_f32_e32 v72, v73, v80
	v_mul_f32_e32 v73, v75, v75
	v_fmac_f32_e32 v89, v94, v94
	v_fmac_f32_e32 v73, v74, v74
	v_add_f32_e32 v88, v89, v88
	v_add_f32_e32 v72, v73, v72
	v_add_f32_e32 v72, v72, v88
	ds_bpermute_b32 v73, v128, v72
	s_waitcnt lgkmcnt(0)
	v_add_f32_e32 v72, v72, v73
	v_mov_b32_e32 v73, v72
	s_nop 1
	v_permlane32_swap_b32_e32 v72, v73
	s_and_saveexec_b64 s[10:11], vcc
	s_cbranch_execz .LBB0_641
	s_waitcnt lgkmcnt(0)
	v_add_f32_e32 v72, v72, v73
	ds_write_b32 v112, v72 offset:512
.LBB0_641:
	s_or_b64 exec, exec, s[10:11]
	v_mul_f32_e32 v72, v85, v85
	s_waitcnt lgkmcnt(0)
	v_mul_f32_e32 v73, v87, v87
	v_mul_f32_e32 v69, v69, v69
	v_fmac_f32_e32 v72, v84, v84
	v_fmac_f32_e32 v73, v86, v86
	v_fmac_f32_e32 v69, v68, v68
	v_mul_f32_e32 v68, v71, v71
	v_add_f32_e32 v72, v72, v73
	v_mul_f32_e32 v73, v77, v77
	v_fmac_f32_e32 v68, v70, v70
	v_mul_f32_e32 v61, v61, v61
	v_fmac_f32_e32 v73, v76, v76
	v_add_f32_e32 v68, v69, v68
	v_fmac_f32_e32 v61, v60, v60
	v_add_f32_e32 v72, v73, v72
	v_mul_f32_e32 v73, v79, v79
	v_add_f32_e32 v60, v61, v68
	v_mul_f32_e32 v61, v63, v63
	v_fmac_f32_e32 v73, v78, v78
	v_fmac_f32_e32 v61, v62, v62
	v_add_f32_e32 v72, v73, v72
	v_add_f32_e32 v60, v61, v60
	v_add_f32_e32 v60, v60, v72
	ds_bpermute_b32 v61, v128, v60
	s_waitcnt lgkmcnt(0)
	v_add_f32_e32 v60, v60, v61
	v_mov_b32_e32 v61, v60
	s_nop 1
	v_permlane32_swap_b32_e32 v60, v61
	s_and_saveexec_b64 s[10:11], vcc
	s_cbranch_execz .LBB0_643
	s_waitcnt lgkmcnt(0)
	v_add_f32_e32 v60, v60, v61
	ds_write_b32 v112, v60 offset:768
; __device__ __forceinline__ void tile_row_ss(const AccT& acc, PG8_LAS float* P, int wr, int wc, int fr, int fq) {
;     ...
;         for (int m = 0; m < 4; ++m) { float ss = 0.f;
; #pragma unroll
;             for (int bj = 0; bj < 2; ++bj) { const f32x4 v0 = acc[ai][bj][m][0], v1 = acc[ai][bj][m][1];
;                 ss += (v0[0] * v0[0] + v0[1] * v0[1]) + (v0[2] * v0[2] + v0[3] * v0[3]) + (v1[0] * v1[0] + v1[1] * v1[1]) + (v1[2] * v1[2] + v1[3] * v1[3]); }
;             ss += __shfl_xor(ss, 16); ss += __shfl_xor(ss, 32);
;             if (fq == 0) P[(ai * HALF + wr * 64 + m * 16 + fr) * 4 + wc] = ss; }
.LBB0_643:
	s_or_b64 exec, exec, s[10:11]
	v_mul_f32_e32 v49, v49, v49
	v_mul_f32_e32 v21, v21, v21
	v_fmac_f32_e32 v49, v48, v48
	v_mul_f32_e32 v48, v51, v51
	v_fmac_f32_e32 v21, v20, v20
	v_mul_f32_e32 v20, v23, v23
	v_fmac_f32_e32 v48, v50, v50
	v_mul_f32_e32 v45, v45, v45
	v_fmac_f32_e32 v20, v22, v22
	v_mul_f32_e32 v13, v13, v13
	v_add_f32_e32 v48, v49, v48
	v_fmac_f32_e32 v45, v44, v44
	v_add_f32_e32 v20, v21, v20
	v_fmac_f32_e32 v13, v12, v12
	v_add_f32_e32 v44, v45, v48
	v_mul_f32_e32 v45, v47, v47
	v_add_f32_e32 v12, v13, v20
	v_mul_f32_e32 v13, v15, v15
	v_fmac_f32_e32 v45, v46, v46
	v_fmac_f32_e32 v13, v14, v14
	v_add_f32_e32 v44, v45, v44
	v_add_f32_e32 v12, v13, v12
	v_add_f32_e32 v12, v12, v44
	ds_bpermute_b32 v13, v128, v12
	s_waitcnt lgkmcnt(0)
	v_add_f32_e32 v12, v12, v13
	v_mov_b32_e32 v13, v12
	s_nop 1
	v_permlane32_swap_b32_e32 v12, v13
	s_and_saveexec_b64 s[10:11], vcc
	s_cbranch_execz .LBB0_645
	s_waitcnt lgkmcnt(0)
	v_add_f32_e32 v12, v12, v13
	ds_write_b32 v112, v12 offset:2048
.LBB0_645:
	s_or_b64 exec, exec, s[10:11]
	v_mul_f32_e32 v1, v1, v1
	v_mul_f32_e32 v12, v25, v25
	s_waitcnt lgkmcnt(0)
	v_mul_f32_e32 v13, v27, v27
	v_fmac_f32_e32 v1, v0, v0
	v_mul_f32_e32 v0, v3, v3
	v_fmac_f32_e32 v12, v24, v24
	v_fmac_f32_e32 v13, v26, v26
	v_fmac_f32_e32 v0, v2, v2
	v_add_f32_e32 v12, v12, v13
	v_mul_f32_e32 v13, v17, v17
	v_add_f32_e32 v0, v1, v0
	v_mul_f32_e32 v1, v53, v53
	v_fmac_f32_e32 v13, v16, v16
	v_fmac_f32_e32 v1, v52, v52
	v_add_f32_e32 v12, v13, v12
	v_mul_f32_e32 v13, v19, v19
	v_add_f32_e32 v0, v1, v0
	v_mul_f32_e32 v1, v55, v55
	v_fmac_f32_e32 v13, v18, v18
	v_fmac_f32_e32 v1, v54, v54
	v_add_f32_e32 v12, v13, v12
	v_add_f32_e32 v0, v1, v0
	v_add_f32_e32 v0, v0, v12
	ds_bpermute_b32 v1, v128, v0
	s_waitcnt lgkmcnt(0)
	v_add_f32_e32 v0, v0, v1
	v_mov_b32_e32 v1, v0
	s_nop 1
	v_permlane32_swap_b32_e32 v0, v1
	s_and_saveexec_b64 s[10:11], vcc
	s_cbranch_execz .LBB0_647
	s_waitcnt lgkmcnt(0)
	v_add_f32_e32 v0, v0, v1
	ds_write_b32 v112, v0 offset:2304
.LBB0_647:
	s_or_b64 exec, exec, s[10:11]
	v_mul_f32_e32 v0, v65, v65
	s_waitcnt lgkmcnt(0)
	v_mul_f32_e32 v1, v67, v67
	v_fmac_f32_e32 v0, v64, v64
	v_fmac_f32_e32 v1, v66, v66
	v_add_f32_e32 v0, v0, v1
	v_mul_f32_e32 v1, v57, v57
	v_fmac_f32_e32 v1, v56, v56
	v_add_f32_e32 v0, v1, v0
	v_mul_f32_e32 v1, v59, v59
	v_fmac_f32_e32 v1, v58, v58
	v_add_f32_e32 v0, v1, v0
	v_mul_f32_e32 v1, v37, v37
	v_mul_f32_e32 v2, v39, v39
	v_fmac_f32_e32 v1, v36, v36
	v_fmac_f32_e32 v2, v38, v38
	v_add_f32_e32 v1, v1, v2
	v_mul_f32_e32 v2, v29, v29
	v_fmac_f32_e32 v2, v28, v28
	v_add_f32_e32 v1, v2, v1
	v_mul_f32_e32 v2, v31, v31
	v_fmac_f32_e32 v2, v30, v30
	v_add_f32_e32 v1, v2, v1
	v_add_f32_e32 v0, v1, v0
	ds_bpermute_b32 v1, v128, v0
	s_waitcnt lgkmcnt(0)
	v_add_f32_e32 v0, v0, v1
	v_mov_b32_e32 v1, v0
	s_nop 1
	v_permlane32_swap_b32_e32 v0, v1
	s_and_saveexec_b64 s[10:11], vcc
	s_cbranch_execz .LBB0_649
	s_waitcnt lgkmcnt(0)
	v_add_f32_e32 v0, v0, v1
	ds_write_b32 v112, v0 offset:2560
.LBB0_649:
	s_or_b64 exec, exec, s[10:11]
	v_mul_f32_e32 v0, v41, v41
	s_waitcnt lgkmcnt(0)
	v_mul_f32_e32 v1, v43, v43
	v_fmac_f32_e32 v0, v40, v40
	v_fmac_f32_e32 v1, v42, v42
	v_add_f32_e32 v0, v0, v1
	v_mul_f32_e32 v1, v33, v33
	v_fmac_f32_e32 v1, v32, v32
	v_add_f32_e32 v0, v1, v0
	v_mul_f32_e32 v1, v35, v35
	v_fmac_f32_e32 v1, v34, v34
	v_add_f32_e32 v0, v1, v0
	v_mul_f32_e32 v1, v9, v9
	v_mul_f32_e32 v2, v11, v11
	v_fmac_f32_e32 v1, v8, v8
	v_fmac_f32_e32 v2, v10, v10
	v_add_f32_e32 v1, v1, v2
	v_mul_f32_e32 v2, v5, v5
	v_fmac_f32_e32 v2, v4, v4
	v_add_f32_e32 v1, v2, v1
	v_mul_f32_e32 v2, v7, v7
	v_fmac_f32_e32 v2, v6, v6
	v_add_f32_e32 v1, v2, v1
	v_add_f32_e32 v0, v1, v0
	ds_bpermute_b32 v1, v128, v0
	s_waitcnt lgkmcnt(0)
	v_add_f32_e32 v0, v0, v1
	v_mov_b32_e32 v1, v0
	s_nop 1
	v_permlane32_swap_b32_e32 v0, v1
	s_and_saveexec_b64 s[10:11], vcc
	s_cbranch_execz .LBB0_651
	s_waitcnt lgkmcnt(0)
	v_add_f32_e32 v0, v0, v1
	ds_write_b32 v112, v0 offset:2816

; __device__ __forceinline__ float bf_lo(unsigned w) { return __uint_as_float(w << 16); }
; __device__ __forceinline__ float bf_hi(unsigned w) { return __uint_as_float(w & 0xffff0000u); }
; #define PG8_STAGE(bufoff, gbase, voff) do { _Pragma("unroll") for (int _i = 0; _i < 2; ++_i) \
;         __builtin_amdgcn_global_load_lds((const unsigned*)((const char*)(gbase) + (voff)[_i]), (PG8_LAS unsigned*)(lds + (bufoff) + ldsw + _i * 8192), 16, 0, 0); } while (0)
; #define PG8_WAIT_V(n) asm volatile("s_waitcnt vmcnt(" #n ")" ::: "memory")
; #define PG8_BAR __builtin_amdgcn_s_barrier()
; __device__ __forceinline__ void acc_from_xb(AccT& acc, const bf16_t* xb, const Unit& u, int wr, int wc, int fr, int fq) {
;     const unsigned off0 = (unsigned)(u.pm * BM + wr * 64 + fr) * DM + u.pn * BM + wc * 32 + 8 * fq;
; #pragma unroll
;     for (int ai = 0; ai < 2; ++ai)
; #pragma unroll
;         for (int m = 0; m < 4; ++m)
; #pragma unroll
;             for (int bj = 0; bj < 2; ++bj) { const u32x4 w = *(const u32x4*)(xb + off0 + (unsigned)(ai * HALF + m * 16) * DM + bj * HALF);
;                 acc[ai][bj][m][0] = (f32x4){bf_lo(w.x), bf_hi(w.x), bf_lo(w.y), bf_hi(w.y)}; acc[ai][bj][m][1] = (f32x4){bf_lo(w.z), bf_hi(w.z), bf_lo(w.w), bf_hi(w.w)}; }
; template <class Epi, class Sched, bool ALIGN_EPI = false, bool SP2 = false>
; __device__ __forceinline__ void gemm_phase(PG8_LAS unsigned char* lds, const Gemm g, const Sched& S, const Epi& E, const int wid) {
;     ...
;     if constexpr (SP2) {
;         PG8_STAGE(PG8_SB(0, 0), cB, voffB); PG8_STAGE(PG8_SB(0, 1), cB + hstepB, voffB); PG8_STAGE(PG8_SA(0, 0), cA, voffA); PG8_STAGE(PG8_SA(0, 1), cA + hstepA, voffA);
;         if (wr == 1) PG8_BAR;
;         PG8_WAIT_V(2); PG8_BAR;
;         PG8_STAGE(PG8_SB(1, 0), cB + kstep, voffB); PG8_STAGE(PG8_SA(1, 0), cA + kstep, voffA); PG8_STAGE(PG8_SB(1, 1), cB + hstepB + kstep, voffB);
;         PG8_WAIT_V(6); PG8_BAR;
.LBB0_820:
	v_readlane_b32 s46, v249, 43
	v_readlane_b32 s47, v249, 44
	s_waitcnt vmcnt(8)
	v_lshlrev_b32_e32 v84, 16, v36
	v_and_b32_e32 v85, 0xffff0000, v36
	v_lshlrev_b32_e32 v86, 16, v37
	v_and_b32_e32 v87, 0xffff0000, v37
	v_lshl_add_u64 v[36:37], s[46:47], 0, v[146:147]
	v_mov_b32_e32 v129, v147
	v_readlane_b32 s48, v249, 39
	v_lshlrev_b32_e32 v76, 16, v38
	v_and_b32_e32 v77, 0xffff0000, v38
	v_lshlrev_b32_e32 v78, 16, v39
	v_and_b32_e32 v79, 0xffff0000, v39
	v_lshl_add_u64 v[38:39], s[46:47], 0, v[128:129]
	v_mov_b32_e32 v133, v147
	v_readlane_b32 s49, v249, 40
	v_lshl_add_u64 v[36:37], v[36:37], 0, s[80:81]
	s_add_i32 m0, s64, 0x18000
	v_lshlrev_b32_e32 v96, 16, v48
	v_and_b32_e32 v97, 0xffff0000, v48
	v_lshlrev_b32_e32 v98, 16, v49
	v_and_b32_e32 v99, 0xffff0000, v49
	v_lshl_add_u64 v[48:49], s[48:49], 0, v[132:133]
	v_mov_b32_e32 v131, v147
	s_waitcnt vmcnt(2)
	s_barrier
	global_load_lds_dwordx4 v[36:37], off
	v_lshl_add_u64 v[36:37], v[38:39], 0, s[80:81]
	s_add_i32 m0, s64, 0x1a000
	s_add_i32 s69, s64, 0x8000
	v_lshlrev_b32_e32 v88, 16, v50
	v_and_b32_e32 v89, 0xffff0000, v50
	v_lshlrev_b32_e32 v90, 16, v51
	v_and_b32_e32 v91, 0xffff0000, v51
	v_lshl_add_u64 v[50:51], s[48:49], 0, v[130:131]
	global_load_lds_dwordx4 v[36:37], off
	v_lshl_add_u64 v[36:37], v[48:49], 0, s[80:81]
	s_mov_b32 m0, s69
	s_add_i32 s70, s64, 0xa000
	v_readlane_b32 s8, v249, 45
	global_load_lds_dwordx4 v[36:37], off
	v_lshl_add_u64 v[36:37], v[50:51], 0, s[80:81]
	s_mov_b32 m0, s70
	v_readlane_b32 s9, v249, 46
	global_load_lds_dwordx4 v[36:37], off
	s_nop 0
	v_lshl_add_u64 v[36:37], s[8:9], 0, v[146:147]
	s_add_i32 m0, s64, 0x1c000
	v_or_b32_e32 v142, s72, v140
	global_load_lds_dwordx4 v[36:37], off
	v_lshl_add_u64 v[36:37], s[8:9], 0, v[128:129]
	s_add_i32 m0, s64, 0x1e000
	v_lshlrev_b32_e32 v161, 6, v142
	global_load_lds_dwordx4 v[36:37], off
	v_and_b32_e32 v162, 48, v138
	s_movk_i32 s4, 0x3c0
	v_and_or_b32 v161, v161, s4, v162
	v_and_b32_e32 v163, 0xfffffc00, v139
	v_readlane_b32 s4, v250, 27
	v_lshlrev_b32_e32 v142, 2, v142
	v_and_b32_e32 v142, 32, v142
	v_add_u32_e32 v170, s4, v163
	v_readlane_b32 s4, v250, 35
	v_bitop3_b32 v161, v161, v170, v142 bitop3:0xde
	v_lshl_or_b32 v142, v140, 6, v162
	v_add_u32_e32 v162, s4, v163
	v_lshlrev_b32_e32 v163, 2, v140
	v_and_b32_e32 v163, 32, v163
	v_bitop3_b32 v142, v142, v162, v163 bitop3:0xde
	v_lshlrev_b32_e32 v162, 14, v134
	v_and_b32_e32 v162, 0xffff8000, v162
	v_lshl_add_u32 v135, v135, 11, v162
	v_and_b32_e32 v134, 1, v134
	v_lshl_or_b32 v134, v134, 6, v135
	v_lshl_add_u32 v134, v160, 1, v134
	v_lshlrev_b32_e32 v160, 14, v136
	v_and_b32_e32 v160, 0xffff8000, v160
	s_waitcnt vmcnt(6)
	v_lshl_add_u32 v137, v137, 11, v160
	v_and_b32_e32 v136, 1, v136
	s_cmp_gt_i32 s5, 0
	v_lshl_or_b32 v136, v136, 6, v137
	v_readlane_b32 s8, v249, 35
	v_lshlrev_b32_e32 v124, 16, v60
	v_and_b32_e32 v125, 0xffff0000, v60
	v_lshlrev_b32_e32 v126, 16, v61
	v_and_b32_e32 v127, 0xffff0000, v61
	v_lshlrev_b32_e32 v120, 16, v62
	v_and_b32_e32 v121, 0xffff0000, v62
	v_lshlrev_b32_e32 v122, 16, v63
	v_and_b32_e32 v123, 0xffff0000, v63
	v_lshlrev_b32_e32 v116, 16, v56
	v_and_b32_e32 v117, 0xffff0000, v56
	v_lshlrev_b32_e32 v118, 16, v57
	v_and_b32_e32 v119, 0xffff0000, v57
	v_lshlrev_b32_e32 v112, 16, v58
	v_and_b32_e32 v113, 0xffff0000, v58
	v_lshlrev_b32_e32 v114, 16, v59
	v_and_b32_e32 v115, 0xffff0000, v59
	v_lshlrev_b32_e32 v108, 16, v52
	v_and_b32_e32 v109, 0xffff0000, v52
	v_lshlrev_b32_e32 v110, 16, v53
	v_and_b32_e32 v111, 0xffff0000, v53
	v_lshlrev_b32_e32 v104, 16, v54
	v_and_b32_e32 v105, 0xffff0000, v54
	v_lshlrev_b32_e32 v106, 16, v55
	v_and_b32_e32 v107, 0xffff0000, v55
	v_lshlrev_b32_e32 v100, 16, v44
	v_and_b32_e32 v101, 0xffff0000, v44
	v_lshlrev_b32_e32 v102, 16, v45
	v_and_b32_e32 v103, 0xffff0000, v45
	v_lshlrev_b32_e32 v92, 16, v46
	v_and_b32_e32 v93, 0xffff0000, v46
	v_lshlrev_b32_e32 v94, 16, v47
	v_and_b32_e32 v95, 0xffff0000, v47
	v_lshlrev_b32_e32 v80, 16, v40
	v_and_b32_e32 v81, 0xffff0000, v40
	v_lshlrev_b32_e32 v82, 16, v41
	v_and_b32_e32 v83, 0xffff0000, v41
	v_lshlrev_b32_e32 v72, 16, v42
	v_and_b32_e32 v73, 0xffff0000, v42
	v_lshlrev_b32_e32 v74, 16, v43
	v_and_b32_e32 v75, 0xffff0000, v43
	v_lshlrev_b32_e32 v68, 16, v20
	v_and_b32_e32 v69, 0xffff0000, v20
	v_lshlrev_b32_e32 v70, 16, v21
	v_and_b32_e32 v71, 0xffff0000, v21
	v_lshlrev_b32_e32 v56, 16, v22
	v_and_b32_e32 v57, 0xffff0000, v22
	v_lshlrev_b32_e32 v58, 16, v23
	v_and_b32_e32 v59, 0xffff0000, v23
	v_lshlrev_b32_e32 v44, 16, v16
	v_and_b32_e32 v45, 0xffff0000, v16
	v_lshlrev_b32_e32 v46, 16, v17
	v_and_b32_e32 v47, 0xffff0000, v17
	v_lshlrev_b32_e32 v40, 16, v18
	v_and_b32_e32 v41, 0xffff0000, v18
	v_lshlrev_b32_e32 v42, 16, v19
	v_and_b32_e32 v43, 0xffff0000, v19
	v_lshlrev_b32_e32 v16, 16, v8
	v_and_b32_e32 v17, 0xffff0000, v8
	v_lshlrev_b32_e32 v18, 16, v9
	v_and_b32_e32 v19, 0xffff0000, v9
	v_lshlrev_b32_e32 v8, 16, v10
	v_and_b32_e32 v9, 0xffff0000, v10
	v_lshlrev_b32_e32 v10, 16, v11
	v_and_b32_e32 v11, 0xffff0000, v11
	v_lshlrev_b32_e32 v20, 16, v12
	v_and_b32_e32 v21, 0xffff0000, v12
	v_lshlrev_b32_e32 v22, 16, v13
	v_and_b32_e32 v23, 0xffff0000, v13
	v_lshlrev_b32_e32 v12, 16, v14
	v_and_b32_e32 v13, 0xffff0000, v14
	v_lshlrev_b32_e32 v14, 16, v15
	v_and_b32_e32 v15, 0xffff0000, v15
	v_lshlrev_b32_e32 v60, 16, v32
	v_and_b32_e32 v61, 0xffff0000, v32
	v_lshlrev_b32_e32 v62, 16, v33
	v_and_b32_e32 v63, 0xffff0000, v33
	v_lshlrev_b32_e32 v48, 16, v34
	v_and_b32_e32 v49, 0xffff0000, v34
	v_lshlrev_b32_e32 v50, 16, v35
	v_and_b32_e32 v51, 0xffff0000, v35
	v_lshlrev_b32_e32 v64, 16, v28
	v_and_b32_e32 v65, 0xffff0000, v28
	v_lshlrev_b32_e32 v66, 16, v29
	v_and_b32_e32 v67, 0xffff0000, v29
	v_lshlrev_b32_e32 v52, 16, v30
	v_and_b32_e32 v53, 0xffff0000, v30
	v_lshlrev_b32_e32 v54, 16, v31
	v_and_b32_e32 v55, 0xffff0000, v31
	v_lshlrev_b32_e32 v32, 16, v24
	v_and_b32_e32 v33, 0xffff0000, v24
	v_lshlrev_b32_e32 v34, 16, v25
	v_and_b32_e32 v35, 0xffff0000, v25
	v_lshlrev_b32_e32 v24, 16, v26
	v_and_b32_e32 v25, 0xffff0000, v26
	v_lshlrev_b32_e32 v26, 16, v27
	v_and_b32_e32 v27, 0xffff0000, v27
	v_lshlrev_b32_e32 v36, 16, v4
	v_and_b32_e32 v37, 0xffff0000, v4
	v_lshlrev_b32_e32 v38, 16, v5
	v_and_b32_e32 v39, 0xffff0000, v5
	v_lshlrev_b32_e32 v28, 16, v6
	v_and_b32_e32 v29, 0xffff0000, v6
	v_lshlrev_b32_e32 v30, 16, v7
	v_and_b32_e32 v31, 0xffff0000, v7
	v_lshlrev_b32_e32 v4, 16, v0
	v_and_b32_e32 v5, 0xffff0000, v0
	v_lshlrev_b32_e32 v6, 16, v1
	v_and_b32_e32 v7, 0xffff0000, v1
	v_lshlrev_b32_e32 v0, 16, v2
	v_and_b32_e32 v1, 0xffff0000, v2
	v_lshlrev_b32_e32 v2, 16, v3
	v_and_b32_e32 v3, 0xffff0000, v3
	s_mov_b32 s72, 0
	s_cselect_b64 s[10:11], -1, 0
	s_add_i32 s71, s5, -2
	v_mov_b32_e32 v135, v147
	v_lshl_add_u32 v136, v143, 1, v136
	v_mov_b32_e32 v137, v147
	v_add_u32_e32 v143, 0, v161
	v_readlane_b32 s4, v248, 12
	s_mov_b32 s68, s8
	s_barrier
	v_readlane_b32 s9, v249, 36
	s_branch .LBB0_822

; __device__ __forceinline__ unsigned pk_bf16(float lo, float hi) { f32x2 v = {lo, hi}; return __builtin_bit_cast(unsigned, __builtin_convertvector(v, bf16v2)); }
; __device__ __forceinline__ void tile_row_ss(const AccT& acc, PG8_LAS float* P, int wr, int wc, int fr, int fq) {
;     ...
;         for (int m = 0; m < 4; ++m) { float ss = 0.f;
; #pragma unroll
;             for (int bj = 0; bj < 2; ++bj) { const f32x4 v0 = acc[ai][bj][m][0], v1 = acc[ai][bj][m][1];
;                 ss += (v0[0] * v0[0] + v0[1] * v0[1]) + (v0[2] * v0[2] + v0[3] * v0[3]) + (v1[0] * v1[0] + v1[1] * v1[1]) + (v1[2] * v1[2] + v1[3] * v1[3]); }
;             ss += __shfl_xor(ss, 16); ss += __shfl_xor(ss, 32);
;             if (fq == 0) P[(ai * HALF + wr * 64 + m * 16 + fr) * 4 + wc] = ss; }
;     __device__ __forceinline__ void fused(AccT& acc, const Unit& u, int wr, int wc, int fr, int fq, PG8_LAS unsigned char* lds, int wid, int lane) const {
;     ...
;                 for (int bj = 0; bj < 2; ++bj) { const f32x4 v0 = acc[ai][bj][m][0], v1 = acc[ai][bj][m][1];
;                     u32x4 w; w.x = pk_bf16(v0[0], v0[1]); w.y = pk_bf16(v0[2], v0[3]); w.z = pk_bf16(v1[0], v1[1]); w.w = pk_bf16(v1[2], v1[3]);
;                     *(u32x4*)(xb + off0 + (unsigned)(ai * HALF + m * 16) * DM + bj * HALF) = w; }
;         tile_row_ss(acc, P, wr, wc, fr, fq);
.LBB0_836:
	s_lshl_b32 s5, s68, 8
	v_readlane_b32 s72, v250, 29
	s_add_i32 s8, s5, s72
	v_or_b32_e32 v128, s8, v140
	v_lshlrev_b32_e32 v128, 10, v128
	s_lshl_b32 s8, s4, 8
	v_add3_u32 v146, s8, v141, v128
	v_cvt_pk_bf16_f32 v128, v124, v125
	v_cvt_pk_bf16_f32 v129, v126, v127
	v_cvt_pk_bf16_f32 v130, v120, v121
	v_cvt_pk_bf16_f32 v131, v122, v123
	v_lshl_add_u64 v[132:133], v[146:147], 1, s[94:95]
	s_mov_b32 s8, 0x8000
	s_barrier
	global_store_dwordx4 v[132:133], v[128:131], off sc1
	v_add_co_u32_e32 v134, vcc, s8, v132
	s_nop 0
	v_cvt_pk_bf16_f32 v128, v116, v117
	v_cvt_pk_bf16_f32 v129, v118, v119
	v_cvt_pk_bf16_f32 v130, v112, v113
	v_cvt_pk_bf16_f32 v131, v114, v115
	global_store_dwordx4 v[132:133], v[128:131], off offset:256 sc1
	v_addc_co_u32_e32 v135, vcc, 0, v133, vcc
	s_nop 0
	v_cvt_pk_bf16_f32 v128, v108, v109
	v_cvt_pk_bf16_f32 v129, v110, v111
	v_cvt_pk_bf16_f32 v130, v104, v105
	v_cvt_pk_bf16_f32 v131, v106, v107
	global_store_dwordx4 v[134:135], v[128:131], off sc1
	s_mov_b32 s52, 0x10000
	s_mov_b32 s8, 0x40000
	v_cvt_pk_bf16_f32 v128, v96, v97
	v_cvt_pk_bf16_f32 v129, v98, v99
	v_cvt_pk_bf16_f32 v130, v88, v89
	v_cvt_pk_bf16_f32 v131, v90, v91
	global_store_dwordx4 v[134:135], v[128:131], off offset:256 sc1
	v_add_co_u32_e32 v134, vcc, s52, v132
	s_nop 0
	v_cvt_pk_bf16_f32 v128, v100, v101
	v_cvt_pk_bf16_f32 v129, v102, v103
	v_cvt_pk_bf16_f32 v130, v92, v93
	v_cvt_pk_bf16_f32 v131, v94, v95
	v_addc_co_u32_e32 v135, vcc, 0, v133, vcc
	global_store_dwordx4 v[134:135], v[128:131], off sc1
	v_mul_f32_e32 v125, v125, v125
	v_mul_f32_e32 v117, v117, v117
	v_cvt_pk_bf16_f32 v128, v80, v81
	v_cvt_pk_bf16_f32 v129, v82, v83
	v_cvt_pk_bf16_f32 v130, v72, v73
	v_cvt_pk_bf16_f32 v131, v74, v75
	global_store_dwordx4 v[134:135], v[128:131], off offset:256 sc1
	v_add_co_u32_e32 v134, vcc, s73, v132
	s_nop 0
	v_cvt_pk_bf16_f32 v128, v84, v85
	v_cvt_pk_bf16_f32 v129, v86, v87
	v_cvt_pk_bf16_f32 v130, v76, v77
	v_cvt_pk_bf16_f32 v131, v78, v79
	v_addc_co_u32_e32 v135, vcc, 0, v133, vcc
	global_store_dwordx4 v[134:135], v[128:131], off sc1
	v_fmac_f32_e32 v125, v124, v124
	v_mul_f32_e32 v124, v127, v127
	v_cvt_pk_bf16_f32 v128, v68, v69
	v_cvt_pk_bf16_f32 v129, v70, v71
	v_cvt_pk_bf16_f32 v130, v56, v57
	v_cvt_pk_bf16_f32 v131, v58, v59
	global_store_dwordx4 v[134:135], v[128:131], off offset:256 sc1
	v_add_co_u32_e32 v134, vcc, s8, v132
	s_nop 0
	v_cvt_pk_bf16_f32 v128, v44, v45
	v_cvt_pk_bf16_f32 v129, v46, v47
	v_cvt_pk_bf16_f32 v130, v40, v41
	v_cvt_pk_bf16_f32 v131, v42, v43
	v_addc_co_u32_e32 v135, vcc, 0, v133, vcc
	global_store_dwordx4 v[134:135], v[128:131], off sc1
	s_mov_b32 s8, 0x48000
	v_fmac_f32_e32 v117, v116, v116
	v_cvt_pk_bf16_f32 v128, v16, v17
	v_cvt_pk_bf16_f32 v129, v18, v19
	v_cvt_pk_bf16_f32 v130, v8, v9
	v_cvt_pk_bf16_f32 v131, v10, v11
	global_store_dwordx4 v[134:135], v[128:131], off offset:256 sc1
	v_add_co_u32_e32 v134, vcc, s8, v132
	s_nop 0
	v_cvt_pk_bf16_f32 v128, v20, v21
	v_cvt_pk_bf16_f32 v129, v22, v23
	v_cvt_pk_bf16_f32 v130, v12, v13
	v_cvt_pk_bf16_f32 v131, v14, v15
	v_addc_co_u32_e32 v135, vcc, 0, v133, vcc
	global_store_dwordx4 v[134:135], v[128:131], off sc1
	s_mov_b32 s8, 0x50000
	v_mul_f32_e32 v116, v119, v119
	v_cvt_pk_bf16_f32 v128, v60, v61
	v_cvt_pk_bf16_f32 v129, v62, v63
	v_cvt_pk_bf16_f32 v130, v48, v49
	v_cvt_pk_bf16_f32 v131, v50, v51
	global_store_dwordx4 v[134:135], v[128:131], off offset:256 sc1
	v_add_co_u32_e32 v134, vcc, s8, v132
	s_nop 0
	v_cvt_pk_bf16_f32 v128, v64, v65
	v_cvt_pk_bf16_f32 v129, v66, v67
	v_cvt_pk_bf16_f32 v130, v52, v53
	v_cvt_pk_bf16_f32 v131, v54, v55
	v_addc_co_u32_e32 v135, vcc, 0, v133, vcc
	global_store_dwordx4 v[134:135], v[128:131], off sc1
	s_mov_b32 s8, 0x58000
	v_fmac_f32_e32 v124, v126, v126
	v_cvt_pk_bf16_f32 v128, v32, v33
	v_cvt_pk_bf16_f32 v129, v34, v35
	v_cvt_pk_bf16_f32 v130, v24, v25
	v_cvt_pk_bf16_f32 v131, v26, v27
	global_store_dwordx4 v[134:135], v[128:131], off offset:256 sc1
	v_add_co_u32_e32 v134, vcc, s8, v132
	s_nop 0
	v_cvt_pk_bf16_f32 v128, v36, v37
	v_cvt_pk_bf16_f32 v129, v38, v39
	v_cvt_pk_bf16_f32 v130, v28, v29
	v_cvt_pk_bf16_f32 v131, v30, v31
	v_addc_co_u32_e32 v135, vcc, 0, v133, vcc
	v_mul_f32_e32 v121, v121, v121
	v_fmac_f32_e32 v116, v118, v118
	v_mul_f32_e32 v113, v113, v113
	global_store_dwordx4 v[134:135], v[128:131], off sc1
	v_add_f32_e32 v124, v125, v124
	v_fmac_f32_e32 v121, v120, v120
	v_and_b32_e32 v129, 64, v168
	v_add_f32_e32 v116, v117, v116
	v_fmac_f32_e32 v113, v112, v112
	v_xor_b32_e32 v128, 16, v168
	v_add_u32_e32 v129, 64, v129
	v_add_f32_e32 v120, v121, v124
	v_mul_f32_e32 v121, v123, v123
	v_add_f32_e32 v112, v113, v116
	v_mul_f32_e32 v113, v115, v115
	v_cmp_lt_i32_e32 vcc, v128, v129
	v_fmac_f32_e32 v121, v122, v122
	v_fmac_f32_e32 v113, v114, v114
	v_cndmask_b32_e32 v128, v168, v128, vcc
	v_add_f32_e32 v120, v121, v120
	v_add_f32_e32 v112, v113, v112
	v_lshlrev_b32_e32 v128, 2, v128
	v_add_f32_e32 v112, v112, v120
	ds_bpermute_b32 v114, v128, v112
	v_xor_b32_e32 v113, 32, v168
	v_cmp_lt_i32_e32 vcc, v113, v129
	v_readlane_b32 s8, v249, 19
	v_cvt_pk_bf16_f32 v130, v4, v5
	v_cndmask_b32_e32 v113, v168, v113, vcc
	v_lshlrev_b32_e32 v113, 2, v113
	s_waitcnt lgkmcnt(0)
	v_add_f32_e32 v114, v112, v114
	v_mov_b32_e32 v115, v114
	s_nop 1
	v_permlane32_swap_b32_e32 v114, v115
	v_cvt_pk_bf16_f32 v131, v6, v7
	v_cvt_pk_bf16_f32 v132, v0, v1
	v_cvt_pk_bf16_f32 v133, v2, v3
	v_cmp_gt_u32_e32 vcc, 16, v138
	v_add_u32_e32 v112, s8, v139
	global_store_dwordx4 v[134:135], v[130:133], off offset:256 sc1
	s_and_saveexec_b64 s[10:11], vcc
	s_mov_b32 s66, 0x20000
	s_movk_i32 s67, 0x2000
	s_mov_b32 s54, 0x12000
	s_mov_b32 s55, 0x14000
	s_mov_b32 s64, 0x16000
	s_movk_i32 s65, 0x4000
	s_movk_i32 s50, 0x6000
	s_mov_b32 s70, 0x1a000
	s_mov_b32 s71, 0xa000
	s_cbranch_execz .LBB0_838
	s_waitcnt lgkmcnt(0)
	v_add_f32_e32 v114, v114, v115
	ds_write_b32 v112, v114
.LBB0_838:
	s_or_b64 exec, exec, s[10:11]
	v_mul_f32_e32 v109, v109, v109
	v_mul_f32_e32 v97, v97, v97
	v_fmac_f32_e32 v109, v108, v108
	v_mul_f32_e32 v108, v111, v111
	v_fmac_f32_e32 v97, v96, v96
	v_mul_f32_e32 v96, v99, v99
	v_fmac_f32_e32 v108, v110, v110
	v_mul_f32_e32 v105, v105, v105
	v_fmac_f32_e32 v96, v98, v98
	v_mul_f32_e32 v89, v89, v89
	v_add_f32_e32 v108, v109, v108
	v_fmac_f32_e32 v105, v104, v104
	v_add_f32_e32 v96, v97, v96
	v_fmac_f32_e32 v89, v88, v88
	v_add_f32_e32 v104, v105, v108
	v_mul_f32_e32 v105, v107, v107
	v_add_f32_e32 v88, v89, v96
	v_mul_f32_e32 v89, v91, v91
	v_fmac_f32_e32 v105, v106, v106
	v_fmac_f32_e32 v89, v90, v90
	v_add_f32_e32 v104, v105, v104
	v_add_f32_e32 v88, v89, v88
	v_add_f32_e32 v88, v88, v104
	ds_bpermute_b32 v89, v128, v88
	s_waitcnt lgkmcnt(0)
	v_add_f32_e32 v88, v88, v89
	v_mov_b32_e32 v89, v88
	s_nop 1
	v_permlane32_swap_b32_e32 v88, v89
	s_and_saveexec_b64 s[10:11], vcc
	v_readlane_b32 s68, v248, 18
	v_readlane_b32 s69, v248, 19
	s_cbranch_execz .LBB0_840
	s_waitcnt lgkmcnt(0)
	v_add_f32_e32 v88, v88, v89
	ds_write_b32 v112, v88 offset:256

; __device__ __forceinline__ void tile_row_ss(const AccT& acc, PG8_LAS float* P, int wr, int wc, int fr, int fq) {
;     ...
;         for (int m = 0; m < 4; ++m) { float ss = 0.f;
; #pragma unroll
;             for (int bj = 0; bj < 2; ++bj) { const f32x4 v0 = acc[ai][bj][m][0], v1 = acc[ai][bj][m][1];
;                 ss += (v0[0] * v0[0] + v0[1] * v0[1]) + (v0[2] * v0[2] + v0[3] * v0[3]) + (v1[0] * v1[0] + v1[1] * v1[1]) + (v1[2] * v1[2] + v1[3] * v1[3]); }
;             ss += __shfl_xor(ss, 16); ss += __shfl_xor(ss, 32);
;             if (fq == 0) P[(ai * HALF + wr * 64 + m * 16 + fr) * 4 + wc] = ss; }
.LBB0_842:
	s_or_b64 exec, exec, s[10:11]
	v_mul_f32_e32 v72, v85, v85
	s_waitcnt lgkmcnt(0)
	v_mul_f32_e32 v73, v87, v87
	v_mul_f32_e32 v69, v69, v69
	v_fmac_f32_e32 v72, v84, v84
	v_fmac_f32_e32 v73, v86, v86
	v_fmac_f32_e32 v69, v68, v68
	v_mul_f32_e32 v68, v71, v71
	v_add_f32_e32 v72, v72, v73
	v_mul_f32_e32 v73, v77, v77
	v_fmac_f32_e32 v68, v70, v70
	v_mul_f32_e32 v57, v57, v57
	v_fmac_f32_e32 v73, v76, v76
	v_add_f32_e32 v68, v69, v68
	v_fmac_f32_e32 v57, v56, v56
	v_add_f32_e32 v72, v73, v72
	v_mul_f32_e32 v73, v79, v79
	v_add_f32_e32 v56, v57, v68
	v_mul_f32_e32 v57, v59, v59
	v_fmac_f32_e32 v73, v78, v78
	v_fmac_f32_e32 v57, v58, v58
	v_add_f32_e32 v72, v73, v72
	v_add_f32_e32 v56, v57, v56
	v_add_f32_e32 v56, v56, v72
	ds_bpermute_b32 v57, v128, v56
	s_waitcnt lgkmcnt(0)
	v_add_f32_e32 v56, v56, v57
	v_mov_b32_e32 v57, v56
	s_nop 1
	v_permlane32_swap_b32_e32 v56, v57
	s_and_saveexec_b64 s[10:11], vcc
	s_cbranch_execz .LBB0_844
	s_waitcnt lgkmcnt(0)
	v_add_f32_e32 v56, v56, v57
	ds_write_b32 v112, v56 offset:768
.LBB0_844:
	s_or_b64 exec, exec, s[10:11]
	v_mul_f32_e32 v45, v45, v45
	v_mul_f32_e32 v17, v17, v17
	v_fmac_f32_e32 v45, v44, v44
	v_mul_f32_e32 v44, v47, v47
	v_fmac_f32_e32 v17, v16, v16
	v_mul_f32_e32 v16, v19, v19
	v_fmac_f32_e32 v44, v46, v46
	v_mul_f32_e32 v41, v41, v41
	v_fmac_f32_e32 v16, v18, v18
	v_mul_f32_e32 v9, v9, v9
	v_add_f32_e32 v44, v45, v44
	v_fmac_f32_e32 v41, v40, v40
	v_add_f32_e32 v16, v17, v16
	v_fmac_f32_e32 v9, v8, v8
	v_add_f32_e32 v40, v41, v44
	v_mul_f32_e32 v41, v43, v43
	v_add_f32_e32 v8, v9, v16
	v_mul_f32_e32 v9, v11, v11
	v_fmac_f32_e32 v41, v42, v42
	v_fmac_f32_e32 v9, v10, v10
	v_add_f32_e32 v40, v41, v40
	v_add_f32_e32 v8, v9, v8
	v_add_f32_e32 v8, v8, v40
	ds_bpermute_b32 v9, v128, v8
	s_waitcnt lgkmcnt(0)
	v_add_f32_e32 v8, v8, v9
	v_mov_b32_e32 v9, v8
	s_nop 1
	v_permlane32_swap_b32_e32 v8, v9
	s_and_saveexec_b64 s[10:11], vcc
	s_cbranch_execz .LBB0_846
	s_waitcnt lgkmcnt(0)
	v_add_f32_e32 v8, v8, v9
	ds_write_b32 v112, v8 offset:2048
.LBB0_846:
	s_or_b64 exec, exec, s[10:11]
	v_mul_f32_e32 v8, v21, v21
	s_waitcnt lgkmcnt(0)
	v_mul_f32_e32 v9, v23, v23
	v_fmac_f32_e32 v8, v20, v20
	v_fmac_f32_e32 v9, v22, v22
	v_add_f32_e32 v8, v8, v9
	v_mul_f32_e32 v9, v13, v13
	v_fmac_f32_e32 v9, v12, v12
	v_add_f32_e32 v8, v9, v8
	v_mul_f32_e32 v9, v15, v15
	v_fmac_f32_e32 v9, v14, v14
	v_add_f32_e32 v8, v9, v8
	v_mul_f32_e32 v9, v61, v61
	v_mul_f32_e32 v10, v63, v63
	v_fmac_f32_e32 v9, v60, v60
	v_fmac_f32_e32 v10, v62, v62
	v_add_f32_e32 v9, v9, v10
	v_mul_f32_e32 v10, v49, v49
	v_fmac_f32_e32 v10, v48, v48
	v_add_f32_e32 v9, v10, v9
	v_mul_f32_e32 v10, v51, v51
	v_fmac_f32_e32 v10, v50, v50
	v_add_f32_e32 v9, v10, v9
	v_add_f32_e32 v8, v9, v8
	ds_bpermute_b32 v9, v128, v8
	s_waitcnt lgkmcnt(0)
	v_add_f32_e32 v8, v8, v9
	v_mov_b32_e32 v9, v8
	s_nop 1
	v_permlane32_swap_b32_e32 v8, v9
	s_and_saveexec_b64 s[10:11], vcc
	s_cbranch_execz .LBB0_848
	s_waitcnt lgkmcnt(0)
	v_add_f32_e32 v8, v8, v9
	ds_write_b32 v112, v8 offset:2304
.LBB0_848:
	s_or_b64 exec, exec, s[10:11]
	v_mul_f32_e32 v8, v65, v65
	s_waitcnt lgkmcnt(0)
	v_mul_f32_e32 v9, v67, v67
	v_fmac_f32_e32 v8, v64, v64
	v_fmac_f32_e32 v9, v66, v66
	v_add_f32_e32 v8, v8, v9
	v_mul_f32_e32 v9, v53, v53
	v_fmac_f32_e32 v9, v52, v52
	v_add_f32_e32 v8, v9, v8
	v_mul_f32_e32 v9, v55, v55
	v_fmac_f32_e32 v9, v54, v54
	v_add_f32_e32 v8, v9, v8
	v_mul_f32_e32 v9, v33, v33
	v_mul_f32_e32 v10, v35, v35
	v_fmac_f32_e32 v9, v32, v32
	v_fmac_f32_e32 v10, v34, v34
	v_add_f32_e32 v9, v9, v10
	v_mul_f32_e32 v10, v25, v25
	v_fmac_f32_e32 v10, v24, v24
	v_add_f32_e32 v9, v10, v9
	v_mul_f32_e32 v10, v27, v27
	v_fmac_f32_e32 v10, v26, v26
	v_add_f32_e32 v9, v10, v9
	v_add_f32_e32 v8, v9, v8
	ds_bpermute_b32 v9, v128, v8
	s_waitcnt lgkmcnt(0)
	v_add_f32_e32 v8, v8, v9
	v_mov_b32_e32 v9, v8
	s_nop 1
	v_permlane32_swap_b32_e32 v8, v9
	s_and_saveexec_b64 s[10:11], vcc
	s_cbranch_execz .LBB0_850
	s_waitcnt lgkmcnt(0)
	v_add_f32_e32 v8, v8, v9
	ds_write_b32 v112, v8 offset:2560
.LBB0_850:
	s_or_b64 exec, exec, s[10:11]
	v_mul_f32_e32 v8, v37, v37
	s_waitcnt lgkmcnt(0)
	v_mul_f32_e32 v9, v39, v39
	v_mul_f32_e32 v5, v5, v5
	v_fmac_f32_e32 v8, v36, v36
	v_fmac_f32_e32 v9, v38, v38
	v_fmac_f32_e32 v5, v4, v4
	v_mul_f32_e32 v4, v7, v7
	v_add_f32_e32 v8, v8, v9
	v_mul_f32_e32 v9, v29, v29
	v_fmac_f32_e32 v4, v6, v6
	v_mul_f32_e32 v1, v1, v1
	v_fmac_f32_e32 v9, v28, v28
	v_add_f32_e32 v4, v5, v4
	v_fmac_f32_e32 v1, v0, v0
	v_add_f32_e32 v8, v9, v8
	v_mul_f32_e32 v9, v31, v31
	v_add_f32_e32 v0, v1, v4
	v_mul_f32_e32 v1, v3, v3
	v_fmac_f32_e32 v9, v30, v30
	v_fmac_f32_e32 v1, v2, v2
	v_add_f32_e32 v8, v9, v8
	v_add_f32_e32 v0, v1, v0
	v_add_f32_e32 v0, v0, v8
	ds_bpermute_b32 v1, v128, v0
	s_waitcnt lgkmcnt(0)
	v_add_f32_e32 v0, v0, v1
	v_mov_b32_e32 v1, v0
	s_nop 1
	v_permlane32_swap_b32_e32 v0, v1
	s_and_saveexec_b64 s[10:11], vcc
	s_cbranch_execz .LBB0_852
	s_waitcnt lgkmcnt(0)
	v_add_f32_e32 v0, v0, v1
	ds_write_b32 v112, v0 offset:2816
